# GDN pre forward substitution: next step LDS row reads issued before the current step's reduction; phase-0 norm rows pipelined; barrier protocol skipped between down-proj head and tail phases
# speedup vs baseline: 1.0466x; 1.0087x over previous
; DI void norm_rows(const Prm& p, int mode, const float* gain, int gw, int ngw, int lane) {
;     bf16_t* XN = (bf16_t*)(p.ws + W_XN);
;     for (int r = gw; r < M; r += ngw) {
;         const float* src = nullptr;
;         if (mode == 0) { if (r < ROW_S) src = p.x_prompt + (size_t)r * D; else if (r < ROW_META) src = p.x_sample + (size_t)(r - ROW_S) * D; else if (r < ROW_PAD) src = p.meta + (size_t)((r - ROW_META) & 15) * D; }
;         else src = xrow(p, r);
;         f32x4 v[4]; float ss = 0.f;
; #pragma unroll
;         for (int j = 0; j < 4; ++j) { v[j] = src ? ((const f32x4*)src)[lane + 64 * j] : (f32x4){0.f, 0.f, 0.f, 0.f}; ss += v[j].x * v[j].x + v[j].y * v[j].y + v[j].z * v[j].z + v[j].w * v[j].w; }
.LBB0_37:
	v_writelane_b32 v247, s68, 44
	s_nop 1
	v_writelane_b32 v247, s69, 45
	v_writelane_b32 v247, s70, 46
	v_writelane_b32 v247, s71, 47
	v_writelane_b32 v247, s72, 48
	v_writelane_b32 v247, s73, 49
	v_writelane_b32 v247, s74, 50
	v_writelane_b32 v247, s75, 51
	v_writelane_b32 v247, s76, 52
	v_writelane_b32 v247, s77, 53
	v_writelane_b32 v247, s78, 54
	v_writelane_b32 v247, s79, 55
	v_writelane_b32 v247, s80, 56
	v_writelane_b32 v247, s81, 57
	v_writelane_b32 v247, s82, 58
	v_writelane_b32 v247, s83, 59
	v_writelane_b32 v247, s42, 60
	s_nop 1
	v_writelane_b32 v247, s43, 61
	s_or_b64 exec, exec, s[10:11]
	s_lshl_b32 s1, s3, 3
	v_writelane_b32 v247, s1, 43
	s_ashr_i32 s0, s2, 6
	v_readlane_b32 s6, v247, 1
	s_add_i32 s4, s0, s1
	s_lshl_b32 s70, s6, 3
	s_cmp_gt_i32 s4, 0x88ff
	v_readlane_b32 s7, v247, 2
	s_cbranch_scc1 .LBB0_53
	s_lshl_b32 s1, s3, 13
	s_lshl_b32 s0, s0, 10
	s_add_i32 s2, s1, s0
	v_readlane_b32 s0, v247, 1
	v_readlane_b32 s1, v247, 2
	s_ashr_i32 s5, s4, 31
	v_readlane_b32 s36, v247, 11
	s_lshl_b32 s15, s0, 13
	s_lshl_b64 s[0:1], s[4:5], 12
	v_readlane_b32 s37, v247, 12
	s_add_u32 s6, s36, s0
	s_addc_u32 s7, s37, s1
	s_ashr_i32 s71, s70, 31
	v_and_b32_e32 v0, 63, v8
	s_lshl_b64 s[10:11], s[70:71], 12
	s_lshl_b64 s[0:1], s[4:5], 11
	v_mov_b32_e32 v3, 0
	v_lshlrev_b32_e32 v2, 4, v0
	v_readlane_b32 s50, v247, 25
	v_readlane_b32 s51, v247, 26
	s_add_u32 s0, s34, s0
	s_addc_u32 s1, s35, s1
	v_lshl_add_u64 v[16:17], s[50:51], 0, v[2:3]
	v_lshlrev_b32_e32 v2, 3, v0
	v_lshl_add_u64 v[2:3], s[0:1], 0, v[2:3]
	s_mov_b64 s[0:1], 0x34a800
	v_lshl_add_u64 v[18:19], v[2:3], 0, s[0:1]
	s_lshl_b64 s[12:13], s[70:71], 11
	s_mov_b32 s19, 0
	v_mov_b32_e32 v20, 0x358637bd
	s_mov_b32 s5, 0x800000
	v_lshlrev_b32_e32 v21, 4, v0
	v_readlane_b32 s38, v247, 13
	v_readlane_b32 s39, v247, 14
	v_readlane_b32 s40, v247, 15
	v_readlane_b32 s41, v247, 16
	v_readlane_b32 s42, v247, 17
	v_readlane_b32 s43, v247, 18
	v_readlane_b32 s44, v247, 19
	v_readlane_b32 s45, v247, 20
	v_readlane_b32 s46, v247, 21
	v_readlane_b32 s47, v247, 22
	v_readlane_b32 s48, v247, 23
	v_readlane_b32 s49, v247, 24
	global_load_dwordx4 v[22:25], v[16:17], off
	global_load_dwordx4 v[36:39], v[16:17], off offset:1024
	global_load_dwordx4 v[40:43], v[16:17], off offset:2048
	global_load_dwordx4 v[44:47], v[16:17], off offset:3072
	s_cmp_lt_i32 s4, 0x8000
	s_mov_b64 s[16:17], s[6:7]
	s_cbranch_scc1 .Lnrp_45
	s_cmpk_gt_u32 s4, 0x87ff
	s_mov_b64 s[0:1], -1
	s_cbranch_scc0 .Lnrp_43
	s_and_b32 s0, s2, 0x3c00
	v_readlane_b32 s36, v247, 11
	s_lshl_b32 s0, s0, 2
	v_readlane_b32 s48, v247, 23
	v_readlane_b32 s49, v247, 24
	s_add_u32 s0, s48, s0
	s_addc_u32 s1, s49, 0
	s_cmpk_lt_u32 s4, 0x8840
	v_readlane_b32 s37, v247, 12
	v_readlane_b32 s38, v247, 13
	v_readlane_b32 s39, v247, 14
	v_readlane_b32 s40, v247, 15
	v_readlane_b32 s41, v247, 16
	v_readlane_b32 s42, v247, 17
	v_readlane_b32 s43, v247, 18
	v_readlane_b32 s44, v247, 19
	v_readlane_b32 s45, v247, 20
	v_readlane_b32 s46, v247, 21
	v_readlane_b32 s47, v247, 22
	v_readlane_b32 s50, v247, 25
	v_readlane_b32 s51, v247, 26
	s_cselect_b32 s17, s1, 0
	s_cselect_b32 s16, s0, 0
	s_mov_b64 s[0:1], 0

; DI void norm_rows(const Prm& p, int mode, const float* gain, int gw, int ngw, int lane) {
;     ...
;     for (int r = gw; r < M; r += ngw) {
;         const float* src = nullptr;
;         if (mode == 0) { if (r < ROW_S) src = p.x_prompt + (size_t)r * D; else if (r < ROW_META) src = p.x_sample + (size_t)(r - ROW_S) * D; else if (r < ROW_PAD) src = p.meta + (size_t)((r - ROW_META) & 15) * D; }
;         else src = xrow(p, r);
;         f32x4 v[4]; float ss = 0.f;
; #pragma unroll
;         for (int j = 0; j < 4; ++j) { v[j] = src ? ((const f32x4*)src)[lane + 64 * j] : (f32x4){0.f, 0.f, 0.f, 0.f}; ss += v[j].x * v[j].x + v[j].y * v[j].y + v[j].z * v[j].z + v[j].w * v[j].w; }
.Lnr_first:
	s_waitcnt vmcnt(0)
	s_branch .Lnr_copy

; DI void norm_rows(const Prm& p, int mode, const float* gain, int gw, int ngw, int lane) {
;     ...
;     for (int r = gw; r < M; r += ngw) {
;         const float* src = nullptr;
;         if (mode == 0) { if (r < ROW_S) src = p.x_prompt + (size_t)r * D; else if (r < ROW_META) src = p.x_sample + (size_t)(r - ROW_S) * D; else if (r < ROW_PAD) src = p.meta + (size_t)((r - ROW_META) & 15) * D; }
;         else src = xrow(p, r);
.Lnr_copy:
	v_mov_b64_e32 v[48:49], v[0:1]
	v_mov_b64_e32 v[50:51], v[2:3]
	v_mov_b64_e32 v[52:53], v[4:5]
	v_mov_b64_e32 v[54:55], v[6:7]
	v_mov_b64_e32 v[56:57], v[8:9]
	v_mov_b64_e32 v[58:59], v[10:11]
	v_mov_b64_e32 v[60:61], v[12:13]
	v_mov_b64_e32 v[62:63], v[14:15]
	s_add_i32 s4, s4, s70
	s_add_i32 s2, s2, s15
	s_add_u32 s6, s6, s10
	s_addc_u32 s7, s7, s11
	s_cmp_gt_i32 s4, 0x88ff
	s_cbranch_scc1 .Lnr_body
	s_cmp_lt_i32 s4, 0x8000
	s_mov_b64 s[16:17], s[6:7]
	s_cbranch_scc1 .Lnrl_45
	s_cmpk_gt_u32 s4, 0x87ff
	s_mov_b64 s[0:1], -1
	s_cbranch_scc0 .Lnrl_43
	s_and_b32 s0, s2, 0x3c00
	v_readlane_b32 s36, v247, 11
	s_lshl_b32 s0, s0, 2
	v_readlane_b32 s48, v247, 23
	v_readlane_b32 s49, v247, 24
	s_add_u32 s0, s48, s0
	s_addc_u32 s1, s49, 0
	s_cmpk_lt_u32 s4, 0x8840
	v_readlane_b32 s37, v247, 12
	v_readlane_b32 s38, v247, 13
	v_readlane_b32 s39, v247, 14
	v_readlane_b32 s40, v247, 15
	v_readlane_b32 s41, v247, 16
	v_readlane_b32 s42, v247, 17
	v_readlane_b32 s43, v247, 18
	v_readlane_b32 s44, v247, 19
	v_readlane_b32 s45, v247, 20
	v_readlane_b32 s46, v247, 21
	v_readlane_b32 s47, v247, 22
	v_readlane_b32 s50, v247, 25
	v_readlane_b32 s51, v247, 26
	s_cselect_b32 s17, s1, 0
	s_cselect_b32 s16, s0, 0
	s_mov_b64 s[0:1], 0

; DI unsigned pk2(float lo, float hi) { f32x2 v = {lo, hi}; bf16x2_t b = __builtin_convertvector(v, bf16x2_t); return __builtin_bit_cast(unsigned, b); }
; DI void norm_rows(const Prm& p, int mode, const float* gain, int gw, int ngw, int lane) {
;     ...
;         f32x4 v[4]; float ss = 0.f;
; #pragma unroll
;         for (int j = 0; j < 4; ++j) { v[j] = src ? ((const f32x4*)src)[lane + 64 * j] : (f32x4){0.f, 0.f, 0.f, 0.f}; ss += v[j].x * v[j].x + v[j].y * v[j].y + v[j].z * v[j].z + v[j].w * v[j].w; }
;         ss = wave_sum(ss); const float rstd = rsqrtf(ss * (1.f / D) + 1e-6f);
; #pragma unroll
;         for (int j = 0; j < 4; ++j) { const f32x4 g = ((const f32x4*)gain)[lane + 64 * j]; u32x2 w; w.x = pk2(v[j].x * rstd * g.x, v[j].y * rstd * g.y); w.y = pk2(v[j].z * rstd * g.z, v[j].w * rstd * g.w);
;             ((u32x2*)(XN + (size_t)r * D))[lane + 64 * j] = w; }
;     }
.Lnr_body:
	s_nop 0
	s_nop 0
	v_mul_f32_e32 v30, v57, v57
	v_mul_f32_e32 v31, v49, v49
	v_mul_f32_e32 v32, v61, v61
	v_pk_mul_f32 v[28:29], v[52:53], v[52:53]
	v_fmac_f32_e32 v30, v56, v56
	v_fmac_f32_e32 v31, v48, v48
	v_pk_mul_f32 v[26:27], v[54:55], v[54:55]
	v_fmac_f32_e32 v32, v60, v60
	v_add_f32_e32 v28, v28, v29
	v_fmac_f32_e32 v30, v58, v58
	v_fmac_f32_e32 v31, v50, v50
	v_fmac_f32_e32 v32, v62, v62
	v_add_f32_e32 v26, v26, v28
	v_fmac_f32_e32 v30, v59, v59
	v_fmac_f32_e32 v31, v51, v51
	v_fmac_f32_e32 v32, v63, v63
	v_add_f32_e32 v26, v27, v26
	v_add_f32_e32 v27, v30, v31
	v_add_f32_e32 v27, v27, v32
	v_add_f32_e32 v26, v27, v26
	s_nop 0
	s_nop 0
	v_add_f32_dpp v26, v26, v26 quad_perm:[1,0,3,2] row_mask:0xf bank_mask:0xf bound_ctrl:1
	s_nop 0
	s_nop 0
	v_add_f32_dpp v26, v26, v26 quad_perm:[2,3,0,1] row_mask:0xf bank_mask:0xf bound_ctrl:1
	s_nop 0
	s_nop 0
	v_add_f32_dpp v26, v26, v26 row_half_mirror row_mask:0xf bank_mask:0xf bound_ctrl:1
	s_nop 1
	v_add_f32_dpp v26, v26, v26 row_mirror row_mask:0xf bank_mask:0xf bound_ctrl:1
	s_nop 0
	v_readlane_b32 s16, v26, 16
	v_readlane_b32 s17, v26, 48
	v_readlane_b32 s0, v26, 0
	v_readlane_b32 s1, v26, 32
	v_mov_b32_e32 v26, s16
	v_mov_b32_e32 v27, s17
	v_pk_add_f32 v[26:27], s[0:1], v[26:27]
	s_nop 0
	v_add_f32_e32 v26, v26, v27
	v_fmamk_f32 v26, v26, 0x3a800000, v20
	v_mul_f32_e32 v27, 0x4b800000, v26
	v_cmp_gt_f32_e32 vcc, s5, v26
	s_nop 1
	v_cndmask_b32_e32 v26, v26, v27, vcc
	v_rsq_f32_e32 v26, v26
	s_nop 0
	v_mul_f32_e32 v27, 0x45800000, v26
	v_cndmask_b32_e32 v26, v26, v27, vcc
	v_pk_mul_f32 v[56:57], v[56:57], v[26:27] op_sel_hi:[1,0]
	v_pk_mul_f32 v[58:59], v[58:59], v[26:27] op_sel_hi:[1,0]
	v_pk_mul_f32 v[48:49], v[48:49], v[26:27] op_sel_hi:[1,0]
	v_pk_mul_f32 v[50:51], v[50:51], v[26:27] op_sel_hi:[1,0]
	v_pk_mul_f32 v[52:53], v[52:53], v[26:27] op_sel_hi:[1,0]
	v_pk_mul_f32 v[54:55], v[54:55], v[26:27] op_sel_hi:[1,0]
	s_nop 0
	v_pk_mul_f32 v[56:57], v[22:23], v[56:57]
	v_pk_mul_f32 v[58:59], v[24:25], v[58:59]
	v_cvt_pk_bf16_f32 v56, v56, v57
	v_cvt_pk_bf16_f32 v57, v58, v59
	global_store_dwordx2 v[18:19], v[56:57], off
	s_nop 0
	s_nop 0
	v_pk_mul_f32 v[48:49], v[36:37], v[48:49]
	v_pk_mul_f32 v[50:51], v[38:39], v[50:51]
	v_cvt_pk_bf16_f32 v48, v48, v49
	v_cvt_pk_bf16_f32 v49, v50, v51
	global_store_dwordx2 v[18:19], v[48:49], off offset:512
	s_nop 0
	v_pk_mul_f32 v[56:57], v[60:61], v[26:27] op_sel_hi:[1,0]
	v_pk_mul_f32 v[58:59], v[62:63], v[26:27] op_sel_hi:[1,0]
	s_nop 0
	v_pk_mul_f32 v[48:49], v[40:41], v[56:57]
	v_pk_mul_f32 v[50:51], v[42:43], v[58:59]
	v_cvt_pk_bf16_f32 v48, v48, v49
	v_cvt_pk_bf16_f32 v49, v50, v51
	global_store_dwordx2 v[18:19], v[48:49], off offset:1024
	s_nop 0
	s_nop 0
	v_pk_mul_f32 v[48:49], v[44:45], v[52:53]
	v_pk_mul_f32 v[50:51], v[46:47], v[54:55]
	v_cvt_pk_bf16_f32 v48, v48, v49
	v_cvt_pk_bf16_f32 v49, v50, v51
	global_store_dwordx2 v[18:19], v[48:49], off offset:1536
	v_lshl_add_u64 v[18:19], v[18:19], 0, s[12:13]
	s_cmp_gt_i32 s4, 0x88ff
	s_cbranch_scc0 .LBB0_39

; __device__ __forceinline__ unsigned xb_ld(unsigned* p)              { return __hip_atomic_load(p, __ATOMIC_RELAXED, __HIP_MEMORY_SCOPE_AGENT); }
; __device__ __forceinline__ unsigned xb_add(unsigned* p, unsigned v) { return __hip_atomic_fetch_add(p, v, __ATOMIC_RELAXED, __HIP_MEMORY_SCOPE_AGENT); }
; #define XB_SPIN(cond, bar) do { unsigned _sp = 0; while (cond) { __builtin_amdgcn_s_sleep(1); \
;     if ((++_sp & 255u) == 0u) { if (xb_ld(&(bar)[XB_TMO])) break; if (_sp > XB_SPIN_CAP) { atomicAdd(&(bar)[XB_TMO], 1u); break; } } } } while (0)
; __device__ __forceinline__ void xcd_barrier(const XcdBarrier& b) {
;     asm volatile("s_waitcnt vmcnt(0)" ::: "memory");
;     __syncthreads();
;     if (threadIdx.x == 0) {
;         unsigned* bar = b.bar;
;         __builtin_amdgcn_s_waitcnt(0);
;         unsigned nloc = b.st[0], nx = b.st[1];
;         if (nloc == 0u) { xcd_barrier_complete(bar, b.x, nloc, nx); b.st[0] = nloc; b.st[1] = nx; }
;         const unsigned old = xb_add(&bar[XB_XSUB(b.x)], 1u);
;         const unsigned gen = old / nloc;
;         if (old + 1u == (gen + 1u) * nloc) {
;             __builtin_amdgcn_fence(__ATOMIC_RELEASE, "agent");
;             asm volatile("s_waitcnt vmcnt(0)" ::: "memory");
;             const unsigned og = xb_add(&bar[XB_TOP], 1u);
;             const unsigned tg = og / nx;
;             if (og + 1u == (tg + 1u) * nx) xb_add(&bar[XB_TOPGEN], 1u);
;             else XB_SPIN(xb_ld(&bar[XB_TOPGEN]) == tg, bar);
;             __builtin_amdgcn_fence(__ATOMIC_ACQUIRE, "agent");
;             xb_add(&bar[XB_XGEN(b.x)], 1u);
;             asm volatile("s_waitcnt vmcnt(0)" ::: "memory");
;         } else {
;             XB_SPIN(xb_ld(&bar[XB_XGEN(b.x)]) == gen, bar);
;             __builtin_amdgcn_fence(__ATOMIC_ACQUIRE, "agent");
;             asm volatile("s_waitcnt vmcnt(0)" ::: "memory");
;         }
;     }
;     __syncthreads();
.LBB0_399:
	s_waitcnt lgkmcnt(0)
	s_barrier
	s_waitcnt vmcnt(0)
	s_barrier
	s_mov_b64 s[0:1], exec
	v_readlane_b32 s4, v247, 3
	v_readlane_b32 s5, v247, 4
	s_and_b64 s[4:5], s[0:1], s[4:5]
	s_mov_b64 exec, s[4:5]
	s_branch .LBB0_451
	s_add_i32 s4, 0, 0x23fe0
	v_mov_b32_e32 v0, s4
	s_waitcnt vmcnt(0) expcnt(0) lgkmcnt(0)
	ds_read_b32 v2, v0
	s_add_i32 s4, 0, 0x23fe4
	v_mov_b32_e32 v0, s4
	ds_read_b32 v0, v0
	s_waitcnt lgkmcnt(1)
	v_cmp_ne_u32_e32 vcc, 0, v2
	s_cbranch_vccnz .LBB0_415
	v_readlane_b32 s4, v247, 1
	v_readlane_b32 s5, v247, 2
	v_readlane_b32 s6, v247, 0
	s_mul_i32 s33, s5, s6
	s_mul_i32 s33, s33, s4
	s_add_u32 s4, s34, 0x101200
	s_addc_u32 s5, s35, 0
	s_add_u32 s6, s34, 0x101400
	s_addc_u32 s7, s35, 0
	s_add_u32 s10, s34, 0x101500
	s_addc_u32 s11, s35, 0
	s_add_u32 s12, s34, 0x101600
	s_addc_u32 s13, s35, 0
	s_add_u32 s18, s34, 0x101700
	s_addc_u32 s19, s35, 0
	s_add_u32 s20, s34, 0x101800
	s_addc_u32 s21, s35, 0
	s_add_u32 s68, s34, 0x101900
	s_addc_u32 s69, s35, 0
	s_add_u32 s72, s34, 0x101a00
	s_addc_u32 s73, s35, 0
	s_add_u32 s84, s34, 0x101b00
	s_addc_u32 s85, s35, 0
	s_add_u32 s88, s34, 0x101c00
	s_addc_u32 s89, s35, 0
	s_add_u32 s92, s34, 0x101d00
	s_addc_u32 s93, s35, 0
	s_add_u32 s94, s34, 0x101e00
	s_addc_u32 s95, s35, 0
	s_add_u32 s96, s34, 0x101f00
	s_addc_u32 s97, s35, 0
	s_add_u32 s16, s34, 0x102000
	s_addc_u32 s17, s35, 0
	s_add_u32 s86, s34, 0x102100
	s_addc_u32 s87, s35, 0
	s_add_u32 s36, s34, 0x102200
	s_addc_u32 s37, s35, 0
	s_add_u32 s38, s34, 0x102300
	s_addc_u32 s39, s35, 0
	s_mov_b32 s46, 1
	v_mov_b32_e32 v16, 0
	s_branch .LBB0_403

; DI bf16_t f2bf(float f) { return (bf16_t)(pk2(f, 0.f) & 0xffffu); }
; DI void gdn_pre_unit(const Prm& p, unsigned char* lds0, int u, int tid, int wid, int lane) {
;     ...
;     if (wid < 4) {
;         const int c = 16 * wid + (lane >> 2), pp = lane & 3; const float beta = gL[64 + c];
;         float Tp[16];
; #pragma unroll
;         for (int j = 0; j < 16; ++j) Tp[j] = 0.f;
; #pragma unroll
;         for (int t = 0; t < 64; ++t) { float a = 0.f;
; #pragma unroll
;             for (int j4 = 0; j4 < (t + 15) / 16; ++j4) { const f32x4 av = *(const f32x4*)(AL + t * 64 + pp * 16 + 4 * j4);
;                 a += av.x * Tp[4 * j4]; a += av.y * Tp[4 * j4 + 1]; a += av.z * Tp[4 * j4 + 2]; a += av.w * Tp[4 * j4 + 3]; }
;             a += __int_as_float(__builtin_amdgcn_update_dpp(0, __float_as_int(a), 0xB1, 0xF, 0xF, true));
;             a += __int_as_float(__builtin_amdgcn_update_dpp(0, __float_as_int(a), 0x4E, 0xF, 0xF, true));
;             const float Tt = (t == c ? 1.f : 0.f) - a;
;             if (pp == (t & 3)) Tp[t >> 2] = Tt;
;             if (pp == 0) tbL[t * GT_STR + c] = f2bf(Tt * beta);
;         }
;     }
.LBB0_1500:
	s_or_b64 exec, exec, s[0:1]
	v_lshl_add_u32 v3, v4, 6, s8
	ds_read_b128 v[6:9], v3 offset:256
	v_cndmask_b32_e32 v5, 0, v5, vcc
	v_cmp_eq_u32_e64 s[0:1], 1, v2
	s_waitcnt lgkmcnt(0)
	v_fma_f32 v6, v5, v6, 0
	v_fmac_f32_e32 v6, 0, v7
	v_fmac_f32_e32 v6, 0, v8
	v_fmac_f32_e32 v6, 0, v9
	ds_read_b128 v[100:103], v3 offset:512
	v_cndmask_b32_e64 v7, 0, 1.0, s[0:1]
	s_nop 0
	v_add_f32_dpp v6, v6, v6 quad_perm:[1,0,3,2] row_mask:0xf bank_mask:0xf bound_ctrl:1
	s_nop 1
	v_add_f32_dpp v6, v6, v6 quad_perm:[2,3,0,1] row_mask:0xf bank_mask:0xf bound_ctrl:1
	v_sub_f32_e32 v6, v7, v6
	s_and_saveexec_b64 s[0:1], vcc
	v_mul_f32_e32 v7, v0, v6
	v_cvt_pk_bf16_f32 v7, v7, s0
	ds_write_b16 v1, v7 offset:144
	s_or_b64 exec, exec, s[0:1]
	v_cmp_eq_u32_e64 s[4:5], 1, v4
	v_cmp_eq_u32_e64 s[0:1], 2, v2
	s_nop 0
	v_cndmask_b32_e64 v5, v5, v6, s[4:5]
	s_waitcnt lgkmcnt(1)
	v_fma_f32 v6, v5, v100, 0
	v_fmac_f32_e32 v6, 0, v101
	v_fmac_f32_e32 v6, 0, v102
	v_fmac_f32_e32 v6, 0, v103
	ds_read_b128 v[100:103], v3 offset:768
	v_cndmask_b32_e64 v7, 0, 1.0, s[0:1]
	s_nop 0
	v_add_f32_dpp v6, v6, v6 quad_perm:[1,0,3,2] row_mask:0xf bank_mask:0xf bound_ctrl:1
	s_nop 1
	v_add_f32_dpp v6, v6, v6 quad_perm:[2,3,0,1] row_mask:0xf bank_mask:0xf bound_ctrl:1
	v_sub_f32_e32 v6, v7, v6
	s_and_saveexec_b64 s[0:1], vcc
	v_mul_f32_e32 v7, v0, v6
	v_cvt_pk_bf16_f32 v7, v7, s0
	ds_write_b16 v1, v7 offset:288
	s_or_b64 exec, exec, s[0:1]
	v_cmp_eq_u32_e64 s[6:7], 2, v4
	v_cmp_eq_u32_e64 s[0:1], 3, v2
	s_nop 0
	v_cndmask_b32_e64 v5, v5, v6, s[6:7]
	s_waitcnt lgkmcnt(1)
	v_fma_f32 v6, v5, v100, 0
	v_fmac_f32_e32 v6, 0, v101
	v_fmac_f32_e32 v6, 0, v102
	v_fmac_f32_e32 v6, 0, v103
	ds_read_b128 v[100:103], v3 offset:1024
	v_cndmask_b32_e64 v7, 0, 1.0, s[0:1]
	s_nop 0
	v_add_f32_dpp v6, v6, v6 quad_perm:[1,0,3,2] row_mask:0xf bank_mask:0xf bound_ctrl:1
	s_nop 1
	v_add_f32_dpp v6, v6, v6 quad_perm:[2,3,0,1] row_mask:0xf bank_mask:0xf bound_ctrl:1
	v_sub_f32_e32 v6, v7, v6
	s_and_saveexec_b64 s[0:1], vcc
	v_mul_f32_e32 v7, v0, v6
	v_cvt_pk_bf16_f32 v7, v7, s0
	ds_write_b16 v1, v7 offset:432
	s_or_b64 exec, exec, s[0:1]
	v_cmp_eq_u32_e64 s[8:9], 3, v4
	v_cmp_eq_u32_e64 s[0:1], 4, v2
	s_nop 0
	v_cndmask_b32_e64 v4, v5, v6, s[8:9]
	s_waitcnt lgkmcnt(1)
	v_fma_f32 v5, v4, v100, 0
	v_fmac_f32_e32 v5, 0, v101
	v_fmac_f32_e32 v5, 0, v102
	v_fmac_f32_e32 v5, 0, v103
	ds_read_b128 v[100:103], v3 offset:1280
	v_cndmask_b32_e64 v6, 0, 1.0, s[0:1]
	s_nop 0
	v_add_f32_dpp v5, v5, v5 quad_perm:[1,0,3,2] row_mask:0xf bank_mask:0xf bound_ctrl:1
	s_nop 1
	v_add_f32_dpp v5, v5, v5 quad_perm:[2,3,0,1] row_mask:0xf bank_mask:0xf bound_ctrl:1
	v_sub_f32_e32 v5, v6, v5
	s_and_saveexec_b64 s[0:1], vcc
	v_mul_f32_e32 v6, v0, v5
	v_cvt_pk_bf16_f32 v6, v6, s0
	ds_write_b16 v1, v6 offset:576
	s_or_b64 exec, exec, s[0:1]
	v_cndmask_b32_e32 v5, 0, v5, vcc
	v_cmp_eq_u32_e64 s[0:1], 5, v2
	s_waitcnt lgkmcnt(1)
	v_fma_f32 v6, v4, v100, 0
	v_fmac_f32_e32 v6, v5, v101
	v_fmac_f32_e32 v6, 0, v102
	v_fmac_f32_e32 v6, 0, v103
	ds_read_b128 v[100:103], v3 offset:1536
	v_cndmask_b32_e64 v7, 0, 1.0, s[0:1]
	s_nop 0
	v_add_f32_dpp v6, v6, v6 quad_perm:[1,0,3,2] row_mask:0xf bank_mask:0xf bound_ctrl:1
	s_nop 1
	v_add_f32_dpp v6, v6, v6 quad_perm:[2,3,0,1] row_mask:0xf bank_mask:0xf bound_ctrl:1
	v_sub_f32_e32 v6, v7, v6
	s_and_saveexec_b64 s[0:1], vcc
	v_mul_f32_e32 v7, v0, v6
	v_cvt_pk_bf16_f32 v7, v7, s0
	ds_write_b16 v1, v7 offset:720
	s_or_b64 exec, exec, s[0:1]
	v_cndmask_b32_e64 v5, v5, v6, s[4:5]
	v_cmp_eq_u32_e64 s[0:1], 6, v2
	s_waitcnt lgkmcnt(1)
	v_fma_f32 v6, v4, v100, 0
	v_fmac_f32_e32 v6, v5, v101
	v_fmac_f32_e32 v6, 0, v102
	v_fmac_f32_e32 v6, 0, v103
	ds_read_b128 v[100:103], v3 offset:1792
	v_cndmask_b32_e64 v7, 0, 1.0, s[0:1]
	s_nop 0
	v_add_f32_dpp v6, v6, v6 quad_perm:[1,0,3,2] row_mask:0xf bank_mask:0xf bound_ctrl:1
	s_nop 1
	v_add_f32_dpp v6, v6, v6 quad_perm:[2,3,0,1] row_mask:0xf bank_mask:0xf bound_ctrl:1
	v_sub_f32_e32 v6, v7, v6
	s_and_saveexec_b64 s[0:1], vcc
	v_mul_f32_e32 v7, v0, v6
	v_cvt_pk_bf16_f32 v7, v7, s0
	ds_write_b16 v1, v7 offset:864
	s_or_b64 exec, exec, s[0:1]
	v_cndmask_b32_e64 v5, v5, v6, s[6:7]
	v_cmp_eq_u32_e64 s[0:1], 7, v2
	s_waitcnt lgkmcnt(1)
	v_fma_f32 v6, v4, v100, 0
	v_fmac_f32_e32 v6, v5, v101
	v_fmac_f32_e32 v6, 0, v102
	v_fmac_f32_e32 v6, 0, v103
	ds_read_b128 v[100:103], v3 offset:2048
	v_cndmask_b32_e64 v7, 0, 1.0, s[0:1]
	s_nop 0
	v_add_f32_dpp v6, v6, v6 quad_perm:[1,0,3,2] row_mask:0xf bank_mask:0xf bound_ctrl:1
	s_nop 1
	v_add_f32_dpp v6, v6, v6 quad_perm:[2,3,0,1] row_mask:0xf bank_mask:0xf bound_ctrl:1
	v_sub_f32_e32 v6, v7, v6
	s_and_saveexec_b64 s[0:1], vcc
	v_mul_f32_e32 v7, v0, v6
	v_cvt_pk_bf16_f32 v7, v7, s0
	ds_write_b16 v1, v7 offset:1008
	s_or_b64 exec, exec, s[0:1]
	v_cndmask_b32_e64 v5, v5, v6, s[8:9]
	v_cmp_eq_u32_e64 s[0:1], 8, v2
	s_waitcnt lgkmcnt(1)
	v_fma_f32 v6, v4, v100, 0
	v_fmac_f32_e32 v6, v5, v101
	v_fmac_f32_e32 v6, 0, v102
	v_fmac_f32_e32 v6, 0, v103
	ds_read_b128 v[100:103], v3 offset:2304
	v_cndmask_b32_e64 v7, 0, 1.0, s[0:1]
	s_nop 0
	v_add_f32_dpp v6, v6, v6 quad_perm:[1,0,3,2] row_mask:0xf bank_mask:0xf bound_ctrl:1
	s_nop 1
	v_add_f32_dpp v6, v6, v6 quad_perm:[2,3,0,1] row_mask:0xf bank_mask:0xf bound_ctrl:1
	v_sub_f32_e32 v6, v7, v6
	s_and_saveexec_b64 s[0:1], vcc
	v_mul_f32_e32 v7, v0, v6
	v_cvt_pk_bf16_f32 v7, v7, s0
	ds_write_b16 v1, v7 offset:1152
	s_or_b64 exec, exec, s[0:1]
	v_cndmask_b32_e32 v6, 0, v6, vcc
	v_cmp_eq_u32_e64 s[0:1], 9, v2
	s_waitcnt lgkmcnt(1)
; DI bf16_t f2bf(float f) { return (bf16_t)(pk2(f, 0.f) & 0xffffu); }
; DI void gdn_pre_unit(const Prm& p, unsigned char* lds0, int u, int tid, int wid, int lane) {
;     ...
;     if (wid < 4) {
;         const int c = 16 * wid + (lane >> 2), pp = lane & 3; const float beta = gL[64 + c];
;         float Tp[16];
; #pragma unroll
;         for (int j = 0; j < 16; ++j) Tp[j] = 0.f;
; #pragma unroll
;         for (int t = 0; t < 64; ++t) { float a = 0.f;
; #pragma unroll
;             for (int j4 = 0; j4 < (t + 15) / 16; ++j4) { const f32x4 av = *(const f32x4*)(AL + t * 64 + pp * 16 + 4 * j4);
;                 a += av.x * Tp[4 * j4]; a += av.y * Tp[4 * j4 + 1]; a += av.z * Tp[4 * j4 + 2]; a += av.w * Tp[4 * j4 + 3]; }
;             a += __int_as_float(__builtin_amdgcn_update_dpp(0, __float_as_int(a), 0xB1, 0xF, 0xF, true));
;             a += __int_as_float(__builtin_amdgcn_update_dpp(0, __float_as_int(a), 0x4E, 0xF, 0xF, true));
;             const float Tt = (t == c ? 1.f : 0.f) - a;
;             if (pp == (t & 3)) Tp[t >> 2] = Tt;
;             if (pp == 0) tbL[t * GT_STR + c] = f2bf(Tt * beta);
;         }
;     }
	v_fma_f32 v7, v4, v100, 0
	v_fmac_f32_e32 v7, v5, v101
	v_fmac_f32_e32 v7, v6, v102
	v_fmac_f32_e32 v7, 0, v103
	ds_read_b128 v[100:103], v3 offset:2560
	v_cndmask_b32_e64 v8, 0, 1.0, s[0:1]
	s_nop 0
	v_add_f32_dpp v7, v7, v7 quad_perm:[1,0,3,2] row_mask:0xf bank_mask:0xf bound_ctrl:1
	s_nop 1
	v_add_f32_dpp v7, v7, v7 quad_perm:[2,3,0,1] row_mask:0xf bank_mask:0xf bound_ctrl:1
	v_sub_f32_e32 v7, v8, v7
	s_and_saveexec_b64 s[0:1], vcc
	v_mul_f32_e32 v8, v0, v7
	v_cvt_pk_bf16_f32 v8, v8, s0
	ds_write_b16 v1, v8 offset:1296
	s_or_b64 exec, exec, s[0:1]
	v_cndmask_b32_e64 v6, v6, v7, s[4:5]
	v_cmp_eq_u32_e64 s[0:1], 10, v2
	s_waitcnt lgkmcnt(1)
	v_fma_f32 v7, v4, v100, 0
	v_fmac_f32_e32 v7, v5, v101
	v_fmac_f32_e32 v7, v6, v102
	v_fmac_f32_e32 v7, 0, v103
	ds_read_b128 v[100:103], v3 offset:2816
	v_cndmask_b32_e64 v8, 0, 1.0, s[0:1]
	s_nop 0
	v_add_f32_dpp v7, v7, v7 quad_perm:[1,0,3,2] row_mask:0xf bank_mask:0xf bound_ctrl:1
	s_nop 1
	v_add_f32_dpp v7, v7, v7 quad_perm:[2,3,0,1] row_mask:0xf bank_mask:0xf bound_ctrl:1
	v_sub_f32_e32 v7, v8, v7
	s_and_saveexec_b64 s[0:1], vcc
	v_mul_f32_e32 v8, v0, v7
	v_cvt_pk_bf16_f32 v8, v8, s0
	ds_write_b16 v1, v8 offset:1440
	s_or_b64 exec, exec, s[0:1]
	v_cndmask_b32_e64 v6, v6, v7, s[6:7]
	v_cmp_eq_u32_e64 s[0:1], 11, v2
	s_waitcnt lgkmcnt(1)
	v_fma_f32 v7, v4, v100, 0
	v_fmac_f32_e32 v7, v5, v101
	v_fmac_f32_e32 v7, v6, v102
	v_fmac_f32_e32 v7, 0, v103
	ds_read_b128 v[100:103], v3 offset:3072
	v_cndmask_b32_e64 v8, 0, 1.0, s[0:1]
	s_nop 0
	v_add_f32_dpp v7, v7, v7 quad_perm:[1,0,3,2] row_mask:0xf bank_mask:0xf bound_ctrl:1
	s_nop 1
	v_add_f32_dpp v7, v7, v7 quad_perm:[2,3,0,1] row_mask:0xf bank_mask:0xf bound_ctrl:1
	v_sub_f32_e32 v7, v8, v7
	s_and_saveexec_b64 s[0:1], vcc
	v_mul_f32_e32 v8, v0, v7
	v_cvt_pk_bf16_f32 v8, v8, s0
	ds_write_b16 v1, v8 offset:1584
	s_or_b64 exec, exec, s[0:1]
	v_cndmask_b32_e64 v6, v6, v7, s[8:9]
	v_cmp_eq_u32_e64 s[0:1], 12, v2
	s_waitcnt lgkmcnt(1)
	v_fma_f32 v7, v4, v100, 0
	v_fmac_f32_e32 v7, v5, v101
	v_fmac_f32_e32 v7, v6, v102
	v_fmac_f32_e32 v7, 0, v103
	ds_read_b128 v[100:103], v3 offset:3328
	v_cndmask_b32_e64 v8, 0, 1.0, s[0:1]
	s_nop 0
	v_add_f32_dpp v7, v7, v7 quad_perm:[1,0,3,2] row_mask:0xf bank_mask:0xf bound_ctrl:1
	s_nop 1
	v_add_f32_dpp v7, v7, v7 quad_perm:[2,3,0,1] row_mask:0xf bank_mask:0xf bound_ctrl:1
	v_sub_f32_e32 v7, v8, v7
	s_and_saveexec_b64 s[0:1], vcc
	v_mul_f32_e32 v8, v0, v7
	v_cvt_pk_bf16_f32 v8, v8, s0
	ds_write_b16 v1, v8 offset:1728
	s_or_b64 exec, exec, s[0:1]
	v_cndmask_b32_e32 v7, 0, v7, vcc
	v_cmp_eq_u32_e64 s[0:1], 13, v2
	s_waitcnt lgkmcnt(1)
	v_fma_f32 v8, v4, v100, 0
	v_fmac_f32_e32 v8, v5, v101
	v_fmac_f32_e32 v8, v6, v102
	v_fmac_f32_e32 v8, v7, v103
	ds_read_b128 v[100:103], v3 offset:3584
	v_cndmask_b32_e64 v9, 0, 1.0, s[0:1]
	s_nop 0
	v_add_f32_dpp v8, v8, v8 quad_perm:[1,0,3,2] row_mask:0xf bank_mask:0xf bound_ctrl:1
	s_nop 1
	v_add_f32_dpp v8, v8, v8 quad_perm:[2,3,0,1] row_mask:0xf bank_mask:0xf bound_ctrl:1
	v_sub_f32_e32 v8, v9, v8
	s_and_saveexec_b64 s[0:1], vcc
	v_mul_f32_e32 v9, v0, v8
	v_cvt_pk_bf16_f32 v9, v9, s0
	ds_write_b16 v1, v9 offset:1872
	s_or_b64 exec, exec, s[0:1]
	v_cndmask_b32_e64 v7, v7, v8, s[4:5]
	v_cmp_eq_u32_e64 s[0:1], 14, v2
	s_waitcnt lgkmcnt(1)
	v_fma_f32 v8, v4, v100, 0
	v_fmac_f32_e32 v8, v5, v101
	v_fmac_f32_e32 v8, v6, v102
	v_fmac_f32_e32 v8, v7, v103
	ds_read_b128 v[100:103], v3 offset:3840
	v_cndmask_b32_e64 v9, 0, 1.0, s[0:1]
	s_nop 0
	v_add_f32_dpp v8, v8, v8 quad_perm:[1,0,3,2] row_mask:0xf bank_mask:0xf bound_ctrl:1
	s_nop 1
	v_add_f32_dpp v8, v8, v8 quad_perm:[2,3,0,1] row_mask:0xf bank_mask:0xf bound_ctrl:1
	v_sub_f32_e32 v8, v9, v8
	s_and_saveexec_b64 s[0:1], vcc
	v_mul_f32_e32 v9, v0, v8
	v_cvt_pk_bf16_f32 v9, v9, s0
	ds_write_b16 v1, v9 offset:2016
	s_or_b64 exec, exec, s[0:1]
	v_cndmask_b32_e64 v7, v7, v8, s[6:7]
	v_cmp_eq_u32_e64 s[0:1], 15, v2
	s_waitcnt lgkmcnt(1)
	v_fma_f32 v8, v4, v100, 0
	v_fmac_f32_e32 v8, v5, v101
	v_fmac_f32_e32 v8, v6, v102
	v_fmac_f32_e32 v8, v7, v103
	ds_read_b128 v[100:103], v3 offset:4096
	v_cndmask_b32_e64 v9, 0, 1.0, s[0:1]
	s_nop 0
	v_add_f32_dpp v8, v8, v8 quad_perm:[1,0,3,2] row_mask:0xf bank_mask:0xf bound_ctrl:1
	s_nop 1
	v_add_f32_dpp v8, v8, v8 quad_perm:[2,3,0,1] row_mask:0xf bank_mask:0xf bound_ctrl:1
	v_sub_f32_e32 v8, v9, v8
	s_and_saveexec_b64 s[0:1], vcc
	v_mul_f32_e32 v9, v0, v8
	v_cvt_pk_bf16_f32 v9, v9, s0
	ds_write_b16 v1, v9 offset:2160
	s_or_b64 exec, exec, s[0:1]
	v_cndmask_b32_e64 v7, v7, v8, s[8:9]
	v_cmp_eq_u32_e64 s[0:1], 16, v2
	s_waitcnt lgkmcnt(1)
	v_fma_f32 v8, v4, v100, 0
	v_fmac_f32_e32 v8, v5, v101
	v_fmac_f32_e32 v8, v6, v102
	v_fmac_f32_e32 v8, v7, v103
	ds_read_b128 v[100:103], v3 offset:4352
	ds_read_b128 v[104:107], v3 offset:4368
	v_cndmask_b32_e64 v9, 0, 1.0, s[0:1]
	s_nop 0
	v_add_f32_dpp v8, v8, v8 quad_perm:[1,0,3,2] row_mask:0xf bank_mask:0xf bound_ctrl:1
	s_nop 1
	v_add_f32_dpp v8, v8, v8 quad_perm:[2,3,0,1] row_mask:0xf bank_mask:0xf bound_ctrl:1
	v_sub_f32_e32 v8, v9, v8
	s_and_saveexec_b64 s[0:1], vcc
	v_mul_f32_e32 v9, v0, v8
	v_cvt_pk_bf16_f32 v9, v9, s0
	ds_write_b16 v1, v9 offset:2304
	s_or_b64 exec, exec, s[0:1]
	v_cndmask_b32_e32 v8, 0, v8, vcc
	v_cmp_eq_u32_e64 s[0:1], 17, v2
	s_waitcnt lgkmcnt(2)
	v_fma_f32 v9, v4, v100, 0
	v_fmac_f32_e32 v9, v5, v101
	v_fmac_f32_e32 v9, v6, v102
	v_fmac_f32_e32 v9, v7, v103
	s_waitcnt lgkmcnt(1)
; DI bf16_t f2bf(float f) { return (bf16_t)(pk2(f, 0.f) & 0xffffu); }
; DI void gdn_pre_unit(const Prm& p, unsigned char* lds0, int u, int tid, int wid, int lane) {
;     ...
;     if (wid < 4) {
;         const int c = 16 * wid + (lane >> 2), pp = lane & 3; const float beta = gL[64 + c];
;         float Tp[16];
; #pragma unroll
;         for (int j = 0; j < 16; ++j) Tp[j] = 0.f;
; #pragma unroll
;         for (int t = 0; t < 64; ++t) { float a = 0.f;
; #pragma unroll
;             for (int j4 = 0; j4 < (t + 15) / 16; ++j4) { const f32x4 av = *(const f32x4*)(AL + t * 64 + pp * 16 + 4 * j4);
;                 a += av.x * Tp[4 * j4]; a += av.y * Tp[4 * j4 + 1]; a += av.z * Tp[4 * j4 + 2]; a += av.w * Tp[4 * j4 + 3]; }
;             a += __int_as_float(__builtin_amdgcn_update_dpp(0, __float_as_int(a), 0xB1, 0xF, 0xF, true));
;             a += __int_as_float(__builtin_amdgcn_update_dpp(0, __float_as_int(a), 0x4E, 0xF, 0xF, true));
;             const float Tt = (t == c ? 1.f : 0.f) - a;
;             if (pp == (t & 3)) Tp[t >> 2] = Tt;
;             if (pp == 0) tbL[t * GT_STR + c] = f2bf(Tt * beta);
;         }
;     }
	v_fmac_f32_e32 v9, v8, v104
	v_fmac_f32_e32 v9, 0, v105
	v_fmac_f32_e32 v9, 0, v106
	v_fmac_f32_e32 v9, 0, v107
	ds_read_b128 v[100:103], v3 offset:4608
	ds_read_b128 v[104:107], v3 offset:4624
	v_cndmask_b32_e64 v10, 0, 1.0, s[0:1]
	s_nop 0
	v_add_f32_dpp v9, v9, v9 quad_perm:[1,0,3,2] row_mask:0xf bank_mask:0xf bound_ctrl:1
	s_nop 1
	v_add_f32_dpp v9, v9, v9 quad_perm:[2,3,0,1] row_mask:0xf bank_mask:0xf bound_ctrl:1
	v_sub_f32_e32 v9, v10, v9
	s_and_saveexec_b64 s[0:1], vcc
	v_mul_f32_e32 v10, v0, v9
	v_cvt_pk_bf16_f32 v10, v10, s0
	ds_write_b16 v1, v10 offset:2448
	s_or_b64 exec, exec, s[0:1]
	v_cndmask_b32_e64 v8, v8, v9, s[4:5]
	v_cmp_eq_u32_e64 s[0:1], 18, v2
	s_waitcnt lgkmcnt(2)
	v_fma_f32 v9, v4, v100, 0
	v_fmac_f32_e32 v9, v5, v101
	v_fmac_f32_e32 v9, v6, v102
	v_fmac_f32_e32 v9, v7, v103
	s_waitcnt lgkmcnt(1)
	v_fmac_f32_e32 v9, v8, v104
	v_fmac_f32_e32 v9, 0, v105
	v_fmac_f32_e32 v9, 0, v106
	v_fmac_f32_e32 v9, 0, v107
	ds_read_b128 v[100:103], v3 offset:4864
	ds_read_b128 v[104:107], v3 offset:4880
	v_cndmask_b32_e64 v10, 0, 1.0, s[0:1]
	s_nop 0
	v_add_f32_dpp v9, v9, v9 quad_perm:[1,0,3,2] row_mask:0xf bank_mask:0xf bound_ctrl:1
	s_nop 1
	v_add_f32_dpp v9, v9, v9 quad_perm:[2,3,0,1] row_mask:0xf bank_mask:0xf bound_ctrl:1
	v_sub_f32_e32 v9, v10, v9
	s_and_saveexec_b64 s[0:1], vcc
	v_mul_f32_e32 v10, v0, v9
	v_cvt_pk_bf16_f32 v10, v10, s0
	ds_write_b16 v1, v10 offset:2592
	s_or_b64 exec, exec, s[0:1]
	v_cndmask_b32_e64 v8, v8, v9, s[6:7]
	v_cmp_eq_u32_e64 s[0:1], 19, v2
	s_waitcnt lgkmcnt(2)
	v_fma_f32 v9, v4, v100, 0
	v_fmac_f32_e32 v9, v5, v101
	v_fmac_f32_e32 v9, v6, v102
	v_fmac_f32_e32 v9, v7, v103
	s_waitcnt lgkmcnt(1)
	v_fmac_f32_e32 v9, v8, v104
	v_fmac_f32_e32 v9, 0, v105
	v_fmac_f32_e32 v9, 0, v106
	v_fmac_f32_e32 v9, 0, v107
	ds_read_b128 v[100:103], v3 offset:5120
	ds_read_b128 v[104:107], v3 offset:5136
	v_cndmask_b32_e64 v10, 0, 1.0, s[0:1]
	s_nop 0
	v_add_f32_dpp v9, v9, v9 quad_perm:[1,0,3,2] row_mask:0xf bank_mask:0xf bound_ctrl:1
	s_nop 1
	v_add_f32_dpp v9, v9, v9 quad_perm:[2,3,0,1] row_mask:0xf bank_mask:0xf bound_ctrl:1
	v_sub_f32_e32 v9, v10, v9
	s_and_saveexec_b64 s[0:1], vcc
	v_mul_f32_e32 v10, v0, v9
	v_cvt_pk_bf16_f32 v10, v10, s0
	ds_write_b16 v1, v10 offset:2736
	s_or_b64 exec, exec, s[0:1]
	v_cndmask_b32_e64 v8, v8, v9, s[8:9]
	v_cmp_eq_u32_e64 s[0:1], 20, v2
	s_waitcnt lgkmcnt(2)
	v_fma_f32 v9, v4, v100, 0
	v_fmac_f32_e32 v9, v5, v101
	v_fmac_f32_e32 v9, v6, v102
	v_fmac_f32_e32 v9, v7, v103
	s_waitcnt lgkmcnt(1)
	v_fmac_f32_e32 v9, v8, v104
	v_fmac_f32_e32 v9, 0, v105
	v_fmac_f32_e32 v9, 0, v106
	v_fmac_f32_e32 v9, 0, v107
	ds_read_b128 v[100:103], v3 offset:5376
	ds_read_b128 v[104:107], v3 offset:5392
	v_cndmask_b32_e64 v10, 0, 1.0, s[0:1]
	s_nop 0
	v_add_f32_dpp v9, v9, v9 quad_perm:[1,0,3,2] row_mask:0xf bank_mask:0xf bound_ctrl:1
	s_nop 1
	v_add_f32_dpp v9, v9, v9 quad_perm:[2,3,0,1] row_mask:0xf bank_mask:0xf bound_ctrl:1
	v_sub_f32_e32 v9, v10, v9
	s_and_saveexec_b64 s[0:1], vcc
	v_mul_f32_e32 v10, v0, v9
	v_cvt_pk_bf16_f32 v10, v10, s0
	ds_write_b16 v1, v10 offset:2880
	s_or_b64 exec, exec, s[0:1]
	v_cndmask_b32_e32 v9, 0, v9, vcc
	v_cmp_eq_u32_e64 s[0:1], 21, v2
	s_waitcnt lgkmcnt(2)
	v_fma_f32 v10, v4, v100, 0
	v_fmac_f32_e32 v10, v5, v101
	v_fmac_f32_e32 v10, v6, v102
	v_fmac_f32_e32 v10, v7, v103
	s_waitcnt lgkmcnt(1)
	v_fmac_f32_e32 v10, v8, v104
	v_fmac_f32_e32 v10, v9, v105
	v_fmac_f32_e32 v10, 0, v106
	v_fmac_f32_e32 v10, 0, v107
	ds_read_b128 v[100:103], v3 offset:5632
	ds_read_b128 v[104:107], v3 offset:5648
	v_cndmask_b32_e64 v11, 0, 1.0, s[0:1]
	s_nop 0
	v_add_f32_dpp v10, v10, v10 quad_perm:[1,0,3,2] row_mask:0xf bank_mask:0xf bound_ctrl:1
	s_nop 1
	v_add_f32_dpp v10, v10, v10 quad_perm:[2,3,0,1] row_mask:0xf bank_mask:0xf bound_ctrl:1
	v_sub_f32_e32 v10, v11, v10
	s_and_saveexec_b64 s[0:1], vcc
	v_mul_f32_e32 v11, v0, v10
	v_cvt_pk_bf16_f32 v11, v11, s0
	ds_write_b16 v1, v11 offset:3024
	s_or_b64 exec, exec, s[0:1]
	v_cndmask_b32_e64 v9, v9, v10, s[4:5]
	v_cmp_eq_u32_e64 s[0:1], 22, v2
	s_waitcnt lgkmcnt(2)
	v_fma_f32 v10, v4, v100, 0
	v_fmac_f32_e32 v10, v5, v101
	v_fmac_f32_e32 v10, v6, v102
	v_fmac_f32_e32 v10, v7, v103
	s_waitcnt lgkmcnt(1)
	v_fmac_f32_e32 v10, v8, v104
	v_fmac_f32_e32 v10, v9, v105
	v_fmac_f32_e32 v10, 0, v106
	v_fmac_f32_e32 v10, 0, v107
	ds_read_b128 v[100:103], v3 offset:5888
	ds_read_b128 v[104:107], v3 offset:5904
	v_cndmask_b32_e64 v11, 0, 1.0, s[0:1]
	s_nop 0
	v_add_f32_dpp v10, v10, v10 quad_perm:[1,0,3,2] row_mask:0xf bank_mask:0xf bound_ctrl:1
	s_nop 1
	v_add_f32_dpp v10, v10, v10 quad_perm:[2,3,0,1] row_mask:0xf bank_mask:0xf bound_ctrl:1
	v_sub_f32_e32 v10, v11, v10
	s_and_saveexec_b64 s[0:1], vcc
	v_mul_f32_e32 v11, v0, v10
	v_cvt_pk_bf16_f32 v11, v11, s0
	ds_write_b16 v1, v11 offset:3168
	s_or_b64 exec, exec, s[0:1]
	v_cndmask_b32_e64 v9, v9, v10, s[6:7]
	v_cmp_eq_u32_e64 s[0:1], 23, v2
	s_waitcnt lgkmcnt(2)
	v_fma_f32 v10, v4, v100, 0
	v_fmac_f32_e32 v10, v5, v101
	v_fmac_f32_e32 v10, v6, v102
	v_fmac_f32_e32 v10, v7, v103
	s_waitcnt lgkmcnt(1)
	v_fmac_f32_e32 v10, v8, v104
	v_fmac_f32_e32 v10, v9, v105
	v_fmac_f32_e32 v10, 0, v106
	v_fmac_f32_e32 v10, 0, v107
	ds_read_b128 v[100:103], v3 offset:6144
	ds_read_b128 v[104:107], v3 offset:6160
	v_cndmask_b32_e64 v11, 0, 1.0, s[0:1]
	s_nop 0
	v_add_f32_dpp v10, v10, v10 quad_perm:[1,0,3,2] row_mask:0xf bank_mask:0xf bound_ctrl:1
	s_nop 1
	v_add_f32_dpp v10, v10, v10 quad_perm:[2,3,0,1] row_mask:0xf bank_mask:0xf bound_ctrl:1
	v_sub_f32_e32 v10, v11, v10
	s_and_saveexec_b64 s[0:1], vcc
	v_mul_f32_e32 v11, v0, v10
	v_cvt_pk_bf16_f32 v11, v11, s0
	ds_write_b16 v1, v11 offset:3312
	s_or_b64 exec, exec, s[0:1]
	v_cndmask_b32_e64 v9, v9, v10, s[8:9]
	v_cmp_eq_u32_e64 s[0:1], 24, v2
	s_waitcnt lgkmcnt(2)
; DI bf16_t f2bf(float f) { return (bf16_t)(pk2(f, 0.f) & 0xffffu); }
; DI void gdn_pre_unit(const Prm& p, unsigned char* lds0, int u, int tid, int wid, int lane) {
;     ...
;     if (wid < 4) {
;         const int c = 16 * wid + (lane >> 2), pp = lane & 3; const float beta = gL[64 + c];
;         float Tp[16];
; #pragma unroll
;         for (int j = 0; j < 16; ++j) Tp[j] = 0.f;
; #pragma unroll
;         for (int t = 0; t < 64; ++t) { float a = 0.f;
; #pragma unroll
;             for (int j4 = 0; j4 < (t + 15) / 16; ++j4) { const f32x4 av = *(const f32x4*)(AL + t * 64 + pp * 16 + 4 * j4);
;                 a += av.x * Tp[4 * j4]; a += av.y * Tp[4 * j4 + 1]; a += av.z * Tp[4 * j4 + 2]; a += av.w * Tp[4 * j4 + 3]; }
;             a += __int_as_float(__builtin_amdgcn_update_dpp(0, __float_as_int(a), 0xB1, 0xF, 0xF, true));
;             a += __int_as_float(__builtin_amdgcn_update_dpp(0, __float_as_int(a), 0x4E, 0xF, 0xF, true));
;             const float Tt = (t == c ? 1.f : 0.f) - a;
;             if (pp == (t & 3)) Tp[t >> 2] = Tt;
;             if (pp == 0) tbL[t * GT_STR + c] = f2bf(Tt * beta);
;         }
;     }
	v_fma_f32 v10, v4, v100, 0
	v_fmac_f32_e32 v10, v5, v101
	v_fmac_f32_e32 v10, v6, v102
	v_fmac_f32_e32 v10, v7, v103
	s_waitcnt lgkmcnt(1)
	v_fmac_f32_e32 v10, v8, v104
	v_fmac_f32_e32 v10, v9, v105
	v_fmac_f32_e32 v10, 0, v106
	v_fmac_f32_e32 v10, 0, v107
	ds_read_b128 v[100:103], v3 offset:6400
	ds_read_b128 v[104:107], v3 offset:6416
	v_cndmask_b32_e64 v11, 0, 1.0, s[0:1]
	s_nop 0
	v_add_f32_dpp v10, v10, v10 quad_perm:[1,0,3,2] row_mask:0xf bank_mask:0xf bound_ctrl:1
	s_nop 1
	v_add_f32_dpp v10, v10, v10 quad_perm:[2,3,0,1] row_mask:0xf bank_mask:0xf bound_ctrl:1
	v_sub_f32_e32 v10, v11, v10
	s_and_saveexec_b64 s[0:1], vcc
	v_mul_f32_e32 v11, v0, v10
	v_cvt_pk_bf16_f32 v11, v11, s0
	ds_write_b16 v1, v11 offset:3456
	s_or_b64 exec, exec, s[0:1]
	v_cndmask_b32_e32 v10, 0, v10, vcc
	v_cmp_eq_u32_e64 s[0:1], 25, v2
	s_waitcnt lgkmcnt(2)
	v_fma_f32 v11, v4, v100, 0
	v_fmac_f32_e32 v11, v5, v101
	v_fmac_f32_e32 v11, v6, v102
	v_fmac_f32_e32 v11, v7, v103
	s_waitcnt lgkmcnt(1)
	v_fmac_f32_e32 v11, v8, v104
	v_fmac_f32_e32 v11, v9, v105
	v_fmac_f32_e32 v11, v10, v106
	v_fmac_f32_e32 v11, 0, v107
	ds_read_b128 v[100:103], v3 offset:6656
	ds_read_b128 v[104:107], v3 offset:6672
	v_cndmask_b32_e64 v12, 0, 1.0, s[0:1]
	s_nop 0
	v_add_f32_dpp v11, v11, v11 quad_perm:[1,0,3,2] row_mask:0xf bank_mask:0xf bound_ctrl:1
	s_nop 1
	v_add_f32_dpp v11, v11, v11 quad_perm:[2,3,0,1] row_mask:0xf bank_mask:0xf bound_ctrl:1
	v_sub_f32_e32 v11, v12, v11
	s_and_saveexec_b64 s[0:1], vcc
	v_mul_f32_e32 v12, v0, v11
	v_cvt_pk_bf16_f32 v12, v12, s0
	ds_write_b16 v1, v12 offset:3600
	s_or_b64 exec, exec, s[0:1]
	v_cndmask_b32_e64 v10, v10, v11, s[4:5]
	v_cmp_eq_u32_e64 s[0:1], 26, v2
	s_waitcnt lgkmcnt(2)
	v_fma_f32 v11, v4, v100, 0
	v_fmac_f32_e32 v11, v5, v101
	v_fmac_f32_e32 v11, v6, v102
	v_fmac_f32_e32 v11, v7, v103
	s_waitcnt lgkmcnt(1)
	v_fmac_f32_e32 v11, v8, v104
	v_fmac_f32_e32 v11, v9, v105
	v_fmac_f32_e32 v11, v10, v106
	v_fmac_f32_e32 v11, 0, v107
	ds_read_b128 v[100:103], v3 offset:6912
	ds_read_b128 v[104:107], v3 offset:6928
	v_cndmask_b32_e64 v12, 0, 1.0, s[0:1]
	s_nop 0
	v_add_f32_dpp v11, v11, v11 quad_perm:[1,0,3,2] row_mask:0xf bank_mask:0xf bound_ctrl:1
	s_nop 1
	v_add_f32_dpp v11, v11, v11 quad_perm:[2,3,0,1] row_mask:0xf bank_mask:0xf bound_ctrl:1
	v_sub_f32_e32 v11, v12, v11
	s_and_saveexec_b64 s[0:1], vcc
	v_mul_f32_e32 v12, v0, v11
	v_cvt_pk_bf16_f32 v12, v12, s0
	ds_write_b16 v1, v12 offset:3744
	s_or_b64 exec, exec, s[0:1]
	v_cndmask_b32_e64 v10, v10, v11, s[6:7]
	v_cmp_eq_u32_e64 s[0:1], 27, v2
	s_waitcnt lgkmcnt(2)
	v_fma_f32 v11, v4, v100, 0
	v_fmac_f32_e32 v11, v5, v101
	v_fmac_f32_e32 v11, v6, v102
	v_fmac_f32_e32 v11, v7, v103
	s_waitcnt lgkmcnt(1)
	v_fmac_f32_e32 v11, v8, v104
	v_fmac_f32_e32 v11, v9, v105
	v_fmac_f32_e32 v11, v10, v106
	v_fmac_f32_e32 v11, 0, v107
	ds_read_b128 v[100:103], v3 offset:7168
	ds_read_b128 v[104:107], v3 offset:7184
	v_cndmask_b32_e64 v12, 0, 1.0, s[0:1]
	s_nop 0
	v_add_f32_dpp v11, v11, v11 quad_perm:[1,0,3,2] row_mask:0xf bank_mask:0xf bound_ctrl:1
	s_nop 1
	v_add_f32_dpp v11, v11, v11 quad_perm:[2,3,0,1] row_mask:0xf bank_mask:0xf bound_ctrl:1
	v_sub_f32_e32 v11, v12, v11
	s_and_saveexec_b64 s[0:1], vcc
	v_mul_f32_e32 v12, v0, v11
	v_cvt_pk_bf16_f32 v12, v12, s0
	ds_write_b16 v1, v12 offset:3888
	s_or_b64 exec, exec, s[0:1]
	v_cndmask_b32_e64 v10, v10, v11, s[8:9]
	v_cmp_eq_u32_e64 s[0:1], 28, v2
	s_waitcnt lgkmcnt(2)
	v_fma_f32 v11, v4, v100, 0
	v_fmac_f32_e32 v11, v5, v101
	v_fmac_f32_e32 v11, v6, v102
	v_fmac_f32_e32 v11, v7, v103
	s_waitcnt lgkmcnt(1)
	v_fmac_f32_e32 v11, v8, v104
	v_fmac_f32_e32 v11, v9, v105
	v_fmac_f32_e32 v11, v10, v106
	v_fmac_f32_e32 v11, 0, v107
	ds_read_b128 v[100:103], v3 offset:7424
	ds_read_b128 v[104:107], v3 offset:7440
	v_cndmask_b32_e64 v12, 0, 1.0, s[0:1]
	s_nop 0
	v_add_f32_dpp v11, v11, v11 quad_perm:[1,0,3,2] row_mask:0xf bank_mask:0xf bound_ctrl:1
	s_nop 1
	v_add_f32_dpp v11, v11, v11 quad_perm:[2,3,0,1] row_mask:0xf bank_mask:0xf bound_ctrl:1
	v_sub_f32_e32 v11, v12, v11
	s_and_saveexec_b64 s[0:1], vcc
	v_mul_f32_e32 v12, v0, v11
	v_cvt_pk_bf16_f32 v12, v12, s0
	ds_write_b16 v1, v12 offset:4032
	s_or_b64 exec, exec, s[0:1]
	v_cndmask_b32_e32 v11, 0, v11, vcc
	v_cmp_eq_u32_e64 s[0:1], 29, v2
	s_waitcnt lgkmcnt(2)
	v_fma_f32 v12, v4, v100, 0
	v_fmac_f32_e32 v12, v5, v101
	v_fmac_f32_e32 v12, v6, v102
	v_fmac_f32_e32 v12, v7, v103
	s_waitcnt lgkmcnt(1)
	v_fmac_f32_e32 v12, v8, v104
	v_fmac_f32_e32 v12, v9, v105
	v_fmac_f32_e32 v12, v10, v106
	v_fmac_f32_e32 v12, v11, v107
	ds_read_b128 v[100:103], v3 offset:7680
	ds_read_b128 v[104:107], v3 offset:7696
	v_cndmask_b32_e64 v13, 0, 1.0, s[0:1]
	s_nop 0
	v_add_f32_dpp v12, v12, v12 quad_perm:[1,0,3,2] row_mask:0xf bank_mask:0xf bound_ctrl:1
	s_nop 1
	v_add_f32_dpp v12, v12, v12 quad_perm:[2,3,0,1] row_mask:0xf bank_mask:0xf bound_ctrl:1
	v_sub_f32_e32 v12, v13, v12
	s_and_saveexec_b64 s[0:1], vcc
	v_mul_f32_e32 v13, v0, v12
	v_cvt_pk_bf16_f32 v13, v13, s0
	ds_write_b16 v1, v13 offset:4176
	s_or_b64 exec, exec, s[0:1]
	v_cndmask_b32_e64 v11, v11, v12, s[4:5]
	v_cmp_eq_u32_e64 s[0:1], 30, v2
	s_waitcnt lgkmcnt(2)
	v_fma_f32 v17, v4, v100, 0
	v_fmac_f32_e32 v17, v5, v101
	v_fmac_f32_e32 v17, v6, v102
	v_fmac_f32_e32 v17, v7, v103
	s_waitcnt lgkmcnt(1)
	v_fmac_f32_e32 v17, v8, v104
	v_fmac_f32_e32 v17, v9, v105
	v_fmac_f32_e32 v17, v10, v106
	v_fmac_f32_e32 v17, v11, v107
	ds_read_b128 v[100:103], v3 offset:7936
	ds_read_b128 v[104:107], v3 offset:7952
	v_cndmask_b32_e64 v13, 0, 1.0, s[0:1]
	s_nop 0
	v_add_f32_dpp v12, v17, v17 quad_perm:[1,0,3,2] row_mask:0xf bank_mask:0xf bound_ctrl:1
	s_nop 1
	v_add_f32_dpp v12, v12, v12 quad_perm:[2,3,0,1] row_mask:0xf bank_mask:0xf bound_ctrl:1
	v_sub_f32_e32 v12, v13, v12
	s_and_saveexec_b64 s[0:1], vcc
	v_mul_f32_e32 v13, v0, v12
	v_cvt_pk_bf16_f32 v13, v13, s0
	ds_write_b16 v1, v13 offset:4320
	s_or_b64 exec, exec, s[0:1]
	v_cndmask_b32_e64 v11, v11, v12, s[6:7]
	v_cmp_eq_u32_e64 s[0:1], 31, v2
	s_waitcnt lgkmcnt(2)
; DI bf16_t f2bf(float f) { return (bf16_t)(pk2(f, 0.f) & 0xffffu); }
; DI void gdn_pre_unit(const Prm& p, unsigned char* lds0, int u, int tid, int wid, int lane) {
;     ...
;     if (wid < 4) {
;         const int c = 16 * wid + (lane >> 2), pp = lane & 3; const float beta = gL[64 + c];
;         float Tp[16];
; #pragma unroll
;         for (int j = 0; j < 16; ++j) Tp[j] = 0.f;
; #pragma unroll
;         for (int t = 0; t < 64; ++t) { float a = 0.f;
; #pragma unroll
;             for (int j4 = 0; j4 < (t + 15) / 16; ++j4) { const f32x4 av = *(const f32x4*)(AL + t * 64 + pp * 16 + 4 * j4);
;                 a += av.x * Tp[4 * j4]; a += av.y * Tp[4 * j4 + 1]; a += av.z * Tp[4 * j4 + 2]; a += av.w * Tp[4 * j4 + 3]; }
;             a += __int_as_float(__builtin_amdgcn_update_dpp(0, __float_as_int(a), 0xB1, 0xF, 0xF, true));
;             a += __int_as_float(__builtin_amdgcn_update_dpp(0, __float_as_int(a), 0x4E, 0xF, 0xF, true));
;             const float Tt = (t == c ? 1.f : 0.f) - a;
;             if (pp == (t & 3)) Tp[t >> 2] = Tt;
;             if (pp == 0) tbL[t * GT_STR + c] = f2bf(Tt * beta);
;         }
;     }
	v_fma_f32 v17, v4, v100, 0
	v_fmac_f32_e32 v17, v5, v101
	v_fmac_f32_e32 v17, v6, v102
	v_fmac_f32_e32 v17, v7, v103
	s_waitcnt lgkmcnt(1)
	v_fmac_f32_e32 v17, v8, v104
	v_fmac_f32_e32 v17, v9, v105
	v_fmac_f32_e32 v17, v10, v106
	v_fmac_f32_e32 v17, v11, v107
	ds_read_b128 v[100:103], v3 offset:8192
	ds_read_b128 v[104:107], v3 offset:8208
	v_cndmask_b32_e64 v13, 0, 1.0, s[0:1]
	s_nop 0
	v_add_f32_dpp v12, v17, v17 quad_perm:[1,0,3,2] row_mask:0xf bank_mask:0xf bound_ctrl:1
	s_nop 1
	v_add_f32_dpp v12, v12, v12 quad_perm:[2,3,0,1] row_mask:0xf bank_mask:0xf bound_ctrl:1
	v_sub_f32_e32 v12, v13, v12
	s_and_saveexec_b64 s[0:1], vcc
	v_mul_f32_e32 v13, v0, v12
	v_cvt_pk_bf16_f32 v13, v13, s0
	ds_write_b16 v1, v13 offset:4464
	s_or_b64 exec, exec, s[0:1]
	v_cndmask_b32_e64 v11, v11, v12, s[8:9]
	v_cmp_eq_u32_e64 s[0:1], 32, v2
	s_waitcnt lgkmcnt(2)
	v_fma_f32 v17, v4, v100, 0
	v_fmac_f32_e32 v17, v5, v101
	v_fmac_f32_e32 v17, v6, v102
	v_fmac_f32_e32 v17, v7, v103
	s_waitcnt lgkmcnt(1)
	v_fmac_f32_e32 v17, v8, v104
	v_fmac_f32_e32 v17, v9, v105
	v_fmac_f32_e32 v17, v10, v106
	v_fmac_f32_e32 v17, v11, v107
	ds_read_b128 v[100:103], v3 offset:8448
	ds_read_b128 v[104:107], v3 offset:8464
	ds_read_b128 v[108:111], v3 offset:8480
	v_cndmask_b32_e64 v13, 0, 1.0, s[0:1]
	s_nop 0
	v_add_f32_dpp v12, v17, v17 quad_perm:[1,0,3,2] row_mask:0xf bank_mask:0xf bound_ctrl:1
	s_nop 1
	v_add_f32_dpp v12, v12, v12 quad_perm:[2,3,0,1] row_mask:0xf bank_mask:0xf bound_ctrl:1
	v_sub_f32_e32 v12, v13, v12
	s_and_saveexec_b64 s[0:1], vcc
	v_mul_f32_e32 v13, v0, v12
	v_cvt_pk_bf16_f32 v13, v13, s0
	ds_write_b16 v1, v13 offset:4608
	s_or_b64 exec, exec, s[0:1]
	v_cndmask_b32_e32 v12, 0, v12, vcc
	v_cmp_eq_u32_e64 s[0:1], 33, v2
	s_waitcnt lgkmcnt(3)
	v_fma_f32 v13, v4, v100, 0
	v_fmac_f32_e32 v13, v5, v101
	v_fmac_f32_e32 v13, v6, v102
	v_fmac_f32_e32 v13, v7, v103
	s_waitcnt lgkmcnt(2)
	v_fmac_f32_e32 v13, v8, v104
	v_fmac_f32_e32 v13, v9, v105
	v_fmac_f32_e32 v13, v10, v106
	v_fmac_f32_e32 v13, v11, v107
	s_waitcnt lgkmcnt(1)
	v_fmac_f32_e32 v13, v12, v108
	v_fmac_f32_e32 v13, 0, v109
	v_fmac_f32_e32 v13, 0, v110
	v_fmac_f32_e32 v13, 0, v111
	ds_read_b128 v[100:103], v3 offset:8704
	ds_read_b128 v[104:107], v3 offset:8720
	ds_read_b128 v[108:111], v3 offset:8736
	v_cndmask_b32_e64 v14, 0, 1.0, s[0:1]
	s_nop 0
	v_add_f32_dpp v13, v13, v13 quad_perm:[1,0,3,2] row_mask:0xf bank_mask:0xf bound_ctrl:1
	s_nop 1
	v_add_f32_dpp v13, v13, v13 quad_perm:[2,3,0,1] row_mask:0xf bank_mask:0xf bound_ctrl:1
	v_sub_f32_e32 v13, v14, v13
	s_and_saveexec_b64 s[0:1], vcc
	v_mul_f32_e32 v14, v0, v13
	v_cvt_pk_bf16_f32 v14, v14, s0
	ds_write_b16 v1, v14 offset:4752
	s_or_b64 exec, exec, s[0:1]
	v_cndmask_b32_e64 v12, v12, v13, s[4:5]
	v_cmp_eq_u32_e64 s[0:1], 34, v2
	s_waitcnt lgkmcnt(3)
	v_fma_f32 v13, v4, v100, 0
	v_fmac_f32_e32 v13, v5, v101
	v_fmac_f32_e32 v13, v6, v102
	v_fmac_f32_e32 v13, v7, v103
	s_waitcnt lgkmcnt(2)
	v_fmac_f32_e32 v13, v8, v104
	v_fmac_f32_e32 v13, v9, v105
	v_fmac_f32_e32 v13, v10, v106
	v_fmac_f32_e32 v13, v11, v107
	s_waitcnt lgkmcnt(1)
	v_fmac_f32_e32 v13, v12, v108
	v_fmac_f32_e32 v13, 0, v109
	v_fmac_f32_e32 v13, 0, v110
	v_fmac_f32_e32 v13, 0, v111
	ds_read_b128 v[100:103], v3 offset:8960
	ds_read_b128 v[104:107], v3 offset:8976
	ds_read_b128 v[108:111], v3 offset:8992
	v_cndmask_b32_e64 v14, 0, 1.0, s[0:1]
	s_nop 0
	v_add_f32_dpp v13, v13, v13 quad_perm:[1,0,3,2] row_mask:0xf bank_mask:0xf bound_ctrl:1
	s_nop 1
	v_add_f32_dpp v13, v13, v13 quad_perm:[2,3,0,1] row_mask:0xf bank_mask:0xf bound_ctrl:1
	v_sub_f32_e32 v13, v14, v13
	s_and_saveexec_b64 s[0:1], vcc
	v_mul_f32_e32 v14, v0, v13
	v_cvt_pk_bf16_f32 v14, v14, s0
	ds_write_b16 v1, v14 offset:4896
	s_or_b64 exec, exec, s[0:1]
	v_cndmask_b32_e64 v12, v12, v13, s[6:7]
	v_cmp_eq_u32_e64 s[0:1], 35, v2
	s_waitcnt lgkmcnt(3)
	v_fma_f32 v13, v4, v100, 0
	v_fmac_f32_e32 v13, v5, v101
	v_fmac_f32_e32 v13, v6, v102
	v_fmac_f32_e32 v13, v7, v103
	s_waitcnt lgkmcnt(2)
	v_fmac_f32_e32 v13, v8, v104
	v_fmac_f32_e32 v13, v9, v105
	v_fmac_f32_e32 v13, v10, v106
	v_fmac_f32_e32 v13, v11, v107
	s_waitcnt lgkmcnt(1)
	v_fmac_f32_e32 v13, v12, v108
	v_fmac_f32_e32 v13, 0, v109
	v_fmac_f32_e32 v13, 0, v110
	v_fmac_f32_e32 v13, 0, v111
	ds_read_b128 v[100:103], v3 offset:9216
	ds_read_b128 v[104:107], v3 offset:9232
	ds_read_b128 v[108:111], v3 offset:9248
	v_cndmask_b32_e64 v14, 0, 1.0, s[0:1]
	s_nop 0
	v_add_f32_dpp v13, v13, v13 quad_perm:[1,0,3,2] row_mask:0xf bank_mask:0xf bound_ctrl:1
	s_nop 1
	v_add_f32_dpp v13, v13, v13 quad_perm:[2,3,0,1] row_mask:0xf bank_mask:0xf bound_ctrl:1
	v_sub_f32_e32 v13, v14, v13
	s_and_saveexec_b64 s[0:1], vcc
	v_mul_f32_e32 v14, v0, v13
	v_cvt_pk_bf16_f32 v14, v14, s0
	ds_write_b16 v1, v14 offset:5040
	s_or_b64 exec, exec, s[0:1]
	v_cndmask_b32_e64 v12, v12, v13, s[8:9]
	v_cmp_eq_u32_e64 s[0:1], 36, v2
	s_waitcnt lgkmcnt(3)
	v_fma_f32 v13, v4, v100, 0
	v_fmac_f32_e32 v13, v5, v101
	v_fmac_f32_e32 v13, v6, v102
	v_fmac_f32_e32 v13, v7, v103
	s_waitcnt lgkmcnt(2)
	v_fmac_f32_e32 v13, v8, v104
	v_fmac_f32_e32 v13, v9, v105
	v_fmac_f32_e32 v13, v10, v106
	v_fmac_f32_e32 v13, v11, v107
	s_waitcnt lgkmcnt(1)
	v_fmac_f32_e32 v13, v12, v108
	v_fmac_f32_e32 v13, 0, v109
	v_fmac_f32_e32 v13, 0, v110
	v_fmac_f32_e32 v13, 0, v111
	ds_read_b128 v[100:103], v3 offset:9472
	ds_read_b128 v[104:107], v3 offset:9488
	ds_read_b128 v[108:111], v3 offset:9504
	v_cndmask_b32_e64 v14, 0, 1.0, s[0:1]
	s_nop 0
	v_add_f32_dpp v13, v13, v13 quad_perm:[1,0,3,2] row_mask:0xf bank_mask:0xf bound_ctrl:1
	s_nop 1
	v_add_f32_dpp v13, v13, v13 quad_perm:[2,3,0,1] row_mask:0xf bank_mask:0xf bound_ctrl:1
	v_sub_f32_e32 v13, v14, v13
	s_and_saveexec_b64 s[0:1], vcc
	v_mul_f32_e32 v14, v0, v13
	v_cvt_pk_bf16_f32 v14, v14, s0
	ds_write_b16 v1, v14 offset:5184
	s_or_b64 exec, exec, s[0:1]
	v_cndmask_b32_e32 v13, 0, v13, vcc
	v_cmp_eq_u32_e64 s[0:1], 37, v2
	s_waitcnt lgkmcnt(3)
; DI bf16_t f2bf(float f) { return (bf16_t)(pk2(f, 0.f) & 0xffffu); }
; DI void gdn_pre_unit(const Prm& p, unsigned char* lds0, int u, int tid, int wid, int lane) {
;     ...
;     if (wid < 4) {
;         const int c = 16 * wid + (lane >> 2), pp = lane & 3; const float beta = gL[64 + c];
;         float Tp[16];
; #pragma unroll
;         for (int j = 0; j < 16; ++j) Tp[j] = 0.f;
; #pragma unroll
;         for (int t = 0; t < 64; ++t) { float a = 0.f;
; #pragma unroll
;             for (int j4 = 0; j4 < (t + 15) / 16; ++j4) { const f32x4 av = *(const f32x4*)(AL + t * 64 + pp * 16 + 4 * j4);
;                 a += av.x * Tp[4 * j4]; a += av.y * Tp[4 * j4 + 1]; a += av.z * Tp[4 * j4 + 2]; a += av.w * Tp[4 * j4 + 3]; }
;             a += __int_as_float(__builtin_amdgcn_update_dpp(0, __float_as_int(a), 0xB1, 0xF, 0xF, true));
;             a += __int_as_float(__builtin_amdgcn_update_dpp(0, __float_as_int(a), 0x4E, 0xF, 0xF, true));
;             const float Tt = (t == c ? 1.f : 0.f) - a;
;             if (pp == (t & 3)) Tp[t >> 2] = Tt;
;             if (pp == 0) tbL[t * GT_STR + c] = f2bf(Tt * beta);
;         }
;     }
	v_fma_f32 v14, v4, v100, 0
	v_fmac_f32_e32 v14, v5, v101
	v_fmac_f32_e32 v14, v6, v102
	v_fmac_f32_e32 v14, v7, v103
	s_waitcnt lgkmcnt(2)
	v_fmac_f32_e32 v14, v8, v104
	v_fmac_f32_e32 v14, v9, v105
	v_fmac_f32_e32 v14, v10, v106
	v_fmac_f32_e32 v14, v11, v107
	s_waitcnt lgkmcnt(1)
	v_fmac_f32_e32 v14, v12, v108
	v_fmac_f32_e32 v14, v13, v109
	v_fmac_f32_e32 v14, 0, v110
	v_fmac_f32_e32 v14, 0, v111
	ds_read_b128 v[100:103], v3 offset:9728
	ds_read_b128 v[104:107], v3 offset:9744
	ds_read_b128 v[108:111], v3 offset:9760
	v_cndmask_b32_e64 v15, 0, 1.0, s[0:1]
	s_nop 0
	v_add_f32_dpp v14, v14, v14 quad_perm:[1,0,3,2] row_mask:0xf bank_mask:0xf bound_ctrl:1
	s_nop 1
	v_add_f32_dpp v14, v14, v14 quad_perm:[2,3,0,1] row_mask:0xf bank_mask:0xf bound_ctrl:1
	v_sub_f32_e32 v14, v15, v14
	s_and_saveexec_b64 s[0:1], vcc
	v_mul_f32_e32 v15, v0, v14
	v_cvt_pk_bf16_f32 v15, v15, s0
	ds_write_b16 v1, v15 offset:5328
	s_or_b64 exec, exec, s[0:1]
	v_cndmask_b32_e64 v13, v13, v14, s[4:5]
	v_cmp_eq_u32_e64 s[0:1], 38, v2
	s_waitcnt lgkmcnt(3)
	v_fma_f32 v14, v4, v100, 0
	v_fmac_f32_e32 v14, v5, v101
	v_fmac_f32_e32 v14, v6, v102
	v_fmac_f32_e32 v14, v7, v103
	s_waitcnt lgkmcnt(2)
	v_fmac_f32_e32 v14, v8, v104
	v_fmac_f32_e32 v14, v9, v105
	v_fmac_f32_e32 v14, v10, v106
	v_fmac_f32_e32 v14, v11, v107
	s_waitcnt lgkmcnt(1)
	v_fmac_f32_e32 v14, v12, v108
	v_fmac_f32_e32 v14, v13, v109
	v_fmac_f32_e32 v14, 0, v110
	v_fmac_f32_e32 v14, 0, v111
	ds_read_b128 v[100:103], v3 offset:9984
	ds_read_b128 v[104:107], v3 offset:10000
	ds_read_b128 v[108:111], v3 offset:10016
	v_cndmask_b32_e64 v15, 0, 1.0, s[0:1]
	s_nop 0
	v_add_f32_dpp v14, v14, v14 quad_perm:[1,0,3,2] row_mask:0xf bank_mask:0xf bound_ctrl:1
	s_nop 1
	v_add_f32_dpp v14, v14, v14 quad_perm:[2,3,0,1] row_mask:0xf bank_mask:0xf bound_ctrl:1
	v_sub_f32_e32 v14, v15, v14
	s_and_saveexec_b64 s[0:1], vcc
	v_mul_f32_e32 v15, v0, v14
	v_cvt_pk_bf16_f32 v15, v15, s0
	ds_write_b16 v1, v15 offset:5472
	s_or_b64 exec, exec, s[0:1]
	v_cndmask_b32_e64 v13, v13, v14, s[6:7]
	v_cmp_eq_u32_e64 s[0:1], 39, v2
	s_waitcnt lgkmcnt(3)
	v_fma_f32 v14, v4, v100, 0
	v_fmac_f32_e32 v14, v5, v101
	v_fmac_f32_e32 v14, v6, v102
	v_fmac_f32_e32 v14, v7, v103
	s_waitcnt lgkmcnt(2)
	v_fmac_f32_e32 v14, v8, v104
	v_fmac_f32_e32 v14, v9, v105
	v_fmac_f32_e32 v14, v10, v106
	v_fmac_f32_e32 v14, v11, v107
	s_waitcnt lgkmcnt(1)
	v_fmac_f32_e32 v14, v12, v108
	v_fmac_f32_e32 v14, v13, v109
	v_fmac_f32_e32 v14, 0, v110
	v_fmac_f32_e32 v14, 0, v111
	ds_read_b128 v[100:103], v3 offset:10240
	ds_read_b128 v[104:107], v3 offset:10256
	ds_read_b128 v[108:111], v3 offset:10272
	v_cndmask_b32_e64 v15, 0, 1.0, s[0:1]
	s_nop 0
	v_add_f32_dpp v14, v14, v14 quad_perm:[1,0,3,2] row_mask:0xf bank_mask:0xf bound_ctrl:1
	s_nop 1
	v_add_f32_dpp v14, v14, v14 quad_perm:[2,3,0,1] row_mask:0xf bank_mask:0xf bound_ctrl:1
	v_sub_f32_e32 v14, v15, v14
	s_and_saveexec_b64 s[0:1], vcc
	v_mul_f32_e32 v15, v0, v14
	v_cvt_pk_bf16_f32 v15, v15, s0
	ds_write_b16 v1, v15 offset:5616
	s_or_b64 exec, exec, s[0:1]
	v_cndmask_b32_e64 v13, v13, v14, s[8:9]
	v_cmp_eq_u32_e64 s[0:1], 40, v2
	s_waitcnt lgkmcnt(3)
	v_fma_f32 v14, v4, v100, 0
	v_fmac_f32_e32 v14, v5, v101
	v_fmac_f32_e32 v14, v6, v102
	v_fmac_f32_e32 v14, v7, v103
	s_waitcnt lgkmcnt(2)
	v_fmac_f32_e32 v14, v8, v104
	v_fmac_f32_e32 v14, v9, v105
	v_fmac_f32_e32 v14, v10, v106
	v_fmac_f32_e32 v14, v11, v107
	s_waitcnt lgkmcnt(1)
	v_fmac_f32_e32 v14, v12, v108
	v_fmac_f32_e32 v14, v13, v109
	v_fmac_f32_e32 v14, 0, v110
	v_fmac_f32_e32 v14, 0, v111
	ds_read_b128 v[100:103], v3 offset:10496
	ds_read_b128 v[104:107], v3 offset:10512
	ds_read_b128 v[108:111], v3 offset:10528
	v_cndmask_b32_e64 v15, 0, 1.0, s[0:1]
	s_nop 0
	v_add_f32_dpp v14, v14, v14 quad_perm:[1,0,3,2] row_mask:0xf bank_mask:0xf bound_ctrl:1
	s_nop 1
	v_add_f32_dpp v14, v14, v14 quad_perm:[2,3,0,1] row_mask:0xf bank_mask:0xf bound_ctrl:1
	v_sub_f32_e32 v14, v15, v14
	s_and_saveexec_b64 s[0:1], vcc
	v_mul_f32_e32 v15, v0, v14
	v_cvt_pk_bf16_f32 v15, v15, s0
	ds_write_b16 v1, v15 offset:5760
	s_or_b64 exec, exec, s[0:1]
	v_cndmask_b32_e32 v14, 0, v14, vcc
	v_cmp_eq_u32_e64 s[0:1], 41, v2
	s_waitcnt lgkmcnt(3)
	v_fma_f32 v15, v4, v100, 0
	v_fmac_f32_e32 v15, v5, v101
	v_fmac_f32_e32 v15, v6, v102
	v_fmac_f32_e32 v15, v7, v103
	s_waitcnt lgkmcnt(2)
	v_fmac_f32_e32 v15, v8, v104
	v_fmac_f32_e32 v15, v9, v105
	v_fmac_f32_e32 v15, v10, v106
	v_fmac_f32_e32 v15, v11, v107
	s_waitcnt lgkmcnt(1)
	v_fmac_f32_e32 v15, v12, v108
	v_fmac_f32_e32 v15, v13, v109
	v_fmac_f32_e32 v15, v14, v110
	v_fmac_f32_e32 v15, 0, v111
	ds_read_b128 v[100:103], v3 offset:10752
	ds_read_b128 v[104:107], v3 offset:10768
	ds_read_b128 v[108:111], v3 offset:10784
	v_cndmask_b32_e64 v17, 0, 1.0, s[0:1]
	s_nop 0
	v_add_f32_dpp v15, v15, v15 quad_perm:[1,0,3,2] row_mask:0xf bank_mask:0xf bound_ctrl:1
	s_nop 1
	v_add_f32_dpp v15, v15, v15 quad_perm:[2,3,0,1] row_mask:0xf bank_mask:0xf bound_ctrl:1
	v_sub_f32_e32 v15, v17, v15
	s_and_saveexec_b64 s[0:1], vcc
	v_mul_f32_e32 v17, v0, v15
	v_cvt_pk_bf16_f32 v17, v17, s0
	ds_write_b16 v1, v17 offset:5904
	s_or_b64 exec, exec, s[0:1]
	v_cndmask_b32_e64 v14, v14, v15, s[4:5]
	v_cmp_eq_u32_e64 s[0:1], 42, v2
	s_waitcnt lgkmcnt(3)
	v_fma_f32 v15, v4, v100, 0
	v_fmac_f32_e32 v15, v5, v101
	v_fmac_f32_e32 v15, v6, v102
	v_fmac_f32_e32 v15, v7, v103
	s_waitcnt lgkmcnt(2)
	v_fmac_f32_e32 v15, v8, v104
	v_fmac_f32_e32 v15, v9, v105
	v_fmac_f32_e32 v15, v10, v106
	v_fmac_f32_e32 v15, v11, v107
	s_waitcnt lgkmcnt(1)
; DI bf16_t f2bf(float f) { return (bf16_t)(pk2(f, 0.f) & 0xffffu); }
; DI void gdn_pre_unit(const Prm& p, unsigned char* lds0, int u, int tid, int wid, int lane) {
;     ...
;     if (wid < 4) {
;         const int c = 16 * wid + (lane >> 2), pp = lane & 3; const float beta = gL[64 + c];
;         float Tp[16];
; #pragma unroll
;         for (int j = 0; j < 16; ++j) Tp[j] = 0.f;
; #pragma unroll
;         for (int t = 0; t < 64; ++t) { float a = 0.f;
; #pragma unroll
;             for (int j4 = 0; j4 < (t + 15) / 16; ++j4) { const f32x4 av = *(const f32x4*)(AL + t * 64 + pp * 16 + 4 * j4);
;                 a += av.x * Tp[4 * j4]; a += av.y * Tp[4 * j4 + 1]; a += av.z * Tp[4 * j4 + 2]; a += av.w * Tp[4 * j4 + 3]; }
;             a += __int_as_float(__builtin_amdgcn_update_dpp(0, __float_as_int(a), 0xB1, 0xF, 0xF, true));
;             a += __int_as_float(__builtin_amdgcn_update_dpp(0, __float_as_int(a), 0x4E, 0xF, 0xF, true));
;             const float Tt = (t == c ? 1.f : 0.f) - a;
;             if (pp == (t & 3)) Tp[t >> 2] = Tt;
;             if (pp == 0) tbL[t * GT_STR + c] = f2bf(Tt * beta);
;         }
;     }
	v_fmac_f32_e32 v15, v12, v108
	v_fmac_f32_e32 v15, v13, v109
	v_fmac_f32_e32 v15, v14, v110
	v_fmac_f32_e32 v15, 0, v111
	ds_read_b128 v[100:103], v3 offset:11008
	ds_read_b128 v[104:107], v3 offset:11024
	ds_read_b128 v[108:111], v3 offset:11040
	v_cndmask_b32_e64 v17, 0, 1.0, s[0:1]
	s_nop 0
	v_add_f32_dpp v15, v15, v15 quad_perm:[1,0,3,2] row_mask:0xf bank_mask:0xf bound_ctrl:1
	s_nop 1
	v_add_f32_dpp v15, v15, v15 quad_perm:[2,3,0,1] row_mask:0xf bank_mask:0xf bound_ctrl:1
	v_sub_f32_e32 v15, v17, v15
	s_and_saveexec_b64 s[0:1], vcc
	v_mul_f32_e32 v17, v0, v15
	v_cvt_pk_bf16_f32 v17, v17, s0
	ds_write_b16 v1, v17 offset:6048
	s_or_b64 exec, exec, s[0:1]
	v_cndmask_b32_e64 v14, v14, v15, s[6:7]
	v_cmp_eq_u32_e64 s[0:1], 43, v2
	s_waitcnt lgkmcnt(3)
	v_fma_f32 v15, v4, v100, 0
	v_fmac_f32_e32 v15, v5, v101
	v_fmac_f32_e32 v15, v6, v102
	v_fmac_f32_e32 v15, v7, v103
	s_waitcnt lgkmcnt(2)
	v_fmac_f32_e32 v15, v8, v104
	v_fmac_f32_e32 v15, v9, v105
	v_fmac_f32_e32 v15, v10, v106
	v_fmac_f32_e32 v15, v11, v107
	s_waitcnt lgkmcnt(1)
	v_fmac_f32_e32 v15, v12, v108
	v_fmac_f32_e32 v15, v13, v109
	v_fmac_f32_e32 v15, v14, v110
	v_fmac_f32_e32 v15, 0, v111
	ds_read_b128 v[100:103], v3 offset:11264
	ds_read_b128 v[104:107], v3 offset:11280
	ds_read_b128 v[108:111], v3 offset:11296
	v_cndmask_b32_e64 v17, 0, 1.0, s[0:1]
	s_nop 0
	v_add_f32_dpp v15, v15, v15 quad_perm:[1,0,3,2] row_mask:0xf bank_mask:0xf bound_ctrl:1
	s_nop 1
	v_add_f32_dpp v15, v15, v15 quad_perm:[2,3,0,1] row_mask:0xf bank_mask:0xf bound_ctrl:1
	v_sub_f32_e32 v15, v17, v15
	s_and_saveexec_b64 s[0:1], vcc
	v_mul_f32_e32 v17, v0, v15
	v_cvt_pk_bf16_f32 v17, v17, s0
	ds_write_b16 v1, v17 offset:6192
	s_or_b64 exec, exec, s[0:1]
	v_cndmask_b32_e64 v14, v14, v15, s[8:9]
	v_cmp_eq_u32_e64 s[0:1], 44, v2
	s_waitcnt lgkmcnt(3)
	v_fma_f32 v15, v4, v100, 0
	v_fmac_f32_e32 v15, v5, v101
	v_fmac_f32_e32 v15, v6, v102
	v_fmac_f32_e32 v15, v7, v103
	s_waitcnt lgkmcnt(2)
	v_fmac_f32_e32 v15, v8, v104
	v_fmac_f32_e32 v15, v9, v105
	v_fmac_f32_e32 v15, v10, v106
	v_fmac_f32_e32 v15, v11, v107
	s_waitcnt lgkmcnt(1)
	v_fmac_f32_e32 v15, v12, v108
	v_fmac_f32_e32 v15, v13, v109
	v_fmac_f32_e32 v15, v14, v110
	v_fmac_f32_e32 v15, 0, v111
	ds_read_b128 v[100:103], v3 offset:11520
	ds_read_b128 v[104:107], v3 offset:11536
	ds_read_b128 v[108:111], v3 offset:11552
	v_cndmask_b32_e64 v17, 0, 1.0, s[0:1]
	s_nop 0
	v_add_f32_dpp v15, v15, v15 quad_perm:[1,0,3,2] row_mask:0xf bank_mask:0xf bound_ctrl:1
	s_nop 1
	v_add_f32_dpp v15, v15, v15 quad_perm:[2,3,0,1] row_mask:0xf bank_mask:0xf bound_ctrl:1
	v_sub_f32_e32 v15, v17, v15
	s_and_saveexec_b64 s[0:1], vcc
	v_mul_f32_e32 v17, v0, v15
	v_cvt_pk_bf16_f32 v17, v17, s0
	ds_write_b16 v1, v17 offset:6336
	s_or_b64 exec, exec, s[0:1]
	v_cndmask_b32_e32 v15, 0, v15, vcc
	v_cmp_eq_u32_e64 s[0:1], 45, v2
	s_waitcnt lgkmcnt(3)
	v_fma_f32 v17, v4, v100, 0
	v_fmac_f32_e32 v17, v5, v101
	v_fmac_f32_e32 v17, v6, v102
	v_fmac_f32_e32 v17, v7, v103
	s_waitcnt lgkmcnt(2)
	v_fmac_f32_e32 v17, v8, v104
	v_fmac_f32_e32 v17, v9, v105
	v_fmac_f32_e32 v17, v10, v106
	v_fmac_f32_e32 v17, v11, v107
	s_waitcnt lgkmcnt(1)
	v_fmac_f32_e32 v17, v12, v108
	v_fmac_f32_e32 v17, v13, v109
	v_fmac_f32_e32 v17, v14, v110
	v_fmac_f32_e32 v17, v15, v111
	ds_read_b128 v[100:103], v3 offset:11776
	ds_read_b128 v[104:107], v3 offset:11792
	ds_read_b128 v[108:111], v3 offset:11808
	v_cndmask_b32_e64 v18, 0, 1.0, s[0:1]
	s_nop 0
	v_add_f32_dpp v17, v17, v17 quad_perm:[1,0,3,2] row_mask:0xf bank_mask:0xf bound_ctrl:1
	s_nop 1
	v_add_f32_dpp v17, v17, v17 quad_perm:[2,3,0,1] row_mask:0xf bank_mask:0xf bound_ctrl:1
	v_sub_f32_e32 v17, v18, v17
	s_and_saveexec_b64 s[0:1], vcc
	v_mul_f32_e32 v18, v0, v17
	v_cvt_pk_bf16_f32 v18, v18, s0
	ds_write_b16 v1, v18 offset:6480
	s_or_b64 exec, exec, s[0:1]
	v_cndmask_b32_e64 v15, v15, v17, s[4:5]
	v_cmp_eq_u32_e64 s[0:1], 46, v2
	s_waitcnt lgkmcnt(3)
	v_fma_f32 v17, v4, v100, 0
	v_fmac_f32_e32 v17, v5, v101
	v_fmac_f32_e32 v17, v6, v102
	v_fmac_f32_e32 v17, v7, v103
	s_waitcnt lgkmcnt(2)
	v_fmac_f32_e32 v17, v8, v104
	v_fmac_f32_e32 v17, v9, v105
	v_fmac_f32_e32 v17, v10, v106
	v_fmac_f32_e32 v17, v11, v107
	s_waitcnt lgkmcnt(1)
	v_fmac_f32_e32 v17, v12, v108
	v_fmac_f32_e32 v17, v13, v109
	v_fmac_f32_e32 v17, v14, v110
	v_fmac_f32_e32 v17, v15, v111
	ds_read_b128 v[100:103], v3 offset:12032
	ds_read_b128 v[104:107], v3 offset:12048
	ds_read_b128 v[108:111], v3 offset:12064
	v_cndmask_b32_e64 v18, 0, 1.0, s[0:1]
	s_nop 0
	v_add_f32_dpp v17, v17, v17 quad_perm:[1,0,3,2] row_mask:0xf bank_mask:0xf bound_ctrl:1
	s_nop 1
	v_add_f32_dpp v17, v17, v17 quad_perm:[2,3,0,1] row_mask:0xf bank_mask:0xf bound_ctrl:1
	v_sub_f32_e32 v17, v18, v17
	s_and_saveexec_b64 s[0:1], vcc
	v_mul_f32_e32 v18, v0, v17
	v_cvt_pk_bf16_f32 v18, v18, s0
	ds_write_b16 v1, v18 offset:6624
	s_or_b64 exec, exec, s[0:1]
	v_cndmask_b32_e64 v15, v15, v17, s[6:7]
	v_cmp_eq_u32_e64 s[0:1], 47, v2
	s_waitcnt lgkmcnt(3)
	v_fma_f32 v17, v4, v100, 0
	v_fmac_f32_e32 v17, v5, v101
	v_fmac_f32_e32 v17, v6, v102
	v_fmac_f32_e32 v17, v7, v103
	s_waitcnt lgkmcnt(2)
	v_fmac_f32_e32 v17, v8, v104
	v_fmac_f32_e32 v17, v9, v105
	v_fmac_f32_e32 v17, v10, v106
	v_fmac_f32_e32 v17, v11, v107
	s_waitcnt lgkmcnt(1)
	v_fmac_f32_e32 v17, v12, v108
	v_fmac_f32_e32 v17, v13, v109
	v_fmac_f32_e32 v17, v14, v110
	v_fmac_f32_e32 v17, v15, v111
	ds_read_b128 v[100:103], v3 offset:12288
	ds_read_b128 v[104:107], v3 offset:12304
	ds_read_b128 v[108:111], v3 offset:12320
	v_cndmask_b32_e64 v18, 0, 1.0, s[0:1]
	s_nop 0
	v_add_f32_dpp v17, v17, v17 quad_perm:[1,0,3,2] row_mask:0xf bank_mask:0xf bound_ctrl:1
	s_nop 1
	v_add_f32_dpp v17, v17, v17 quad_perm:[2,3,0,1] row_mask:0xf bank_mask:0xf bound_ctrl:1
	v_sub_f32_e32 v17, v18, v17
	s_and_saveexec_b64 s[0:1], vcc
	v_mul_f32_e32 v18, v0, v17
	v_cvt_pk_bf16_f32 v18, v18, s0
	ds_write_b16 v1, v18 offset:6768
	s_or_b64 exec, exec, s[0:1]
	v_cndmask_b32_e64 v15, v15, v17, s[8:9]
	v_cmp_eq_u32_e64 s[0:1], 48, v2
	s_waitcnt lgkmcnt(3)
; DI bf16_t f2bf(float f) { return (bf16_t)(pk2(f, 0.f) & 0xffffu); }
; DI void gdn_pre_unit(const Prm& p, unsigned char* lds0, int u, int tid, int wid, int lane) {
;     ...
;     if (wid < 4) {
;         const int c = 16 * wid + (lane >> 2), pp = lane & 3; const float beta = gL[64 + c];
;         float Tp[16];
; #pragma unroll
;         for (int j = 0; j < 16; ++j) Tp[j] = 0.f;
; #pragma unroll
;         for (int t = 0; t < 64; ++t) { float a = 0.f;
; #pragma unroll
;             for (int j4 = 0; j4 < (t + 15) / 16; ++j4) { const f32x4 av = *(const f32x4*)(AL + t * 64 + pp * 16 + 4 * j4);
;                 a += av.x * Tp[4 * j4]; a += av.y * Tp[4 * j4 + 1]; a += av.z * Tp[4 * j4 + 2]; a += av.w * Tp[4 * j4 + 3]; }
;             a += __int_as_float(__builtin_amdgcn_update_dpp(0, __float_as_int(a), 0xB1, 0xF, 0xF, true));
;             a += __int_as_float(__builtin_amdgcn_update_dpp(0, __float_as_int(a), 0x4E, 0xF, 0xF, true));
;             const float Tt = (t == c ? 1.f : 0.f) - a;
;             if (pp == (t & 3)) Tp[t >> 2] = Tt;
;             if (pp == 0) tbL[t * GT_STR + c] = f2bf(Tt * beta);
;         }
;     }
	v_fma_f32 v17, v4, v100, 0
	v_fmac_f32_e32 v17, v5, v101
	v_fmac_f32_e32 v17, v6, v102
	v_fmac_f32_e32 v17, v7, v103
	s_waitcnt lgkmcnt(2)
	v_fmac_f32_e32 v17, v8, v104
	v_fmac_f32_e32 v17, v9, v105
	v_fmac_f32_e32 v17, v10, v106
	v_fmac_f32_e32 v17, v11, v107
	s_waitcnt lgkmcnt(1)
	v_fmac_f32_e32 v17, v12, v108
	v_fmac_f32_e32 v17, v13, v109
	v_fmac_f32_e32 v17, v14, v110
	v_fmac_f32_e32 v17, v15, v111
	ds_read_b128 v[100:103], v3 offset:12544
	ds_read_b128 v[104:107], v3 offset:12560
	ds_read_b128 v[108:111], v3 offset:12576
	ds_read_b128 v[112:115], v3 offset:12592
	v_cndmask_b32_e64 v18, 0, 1.0, s[0:1]
	s_nop 0
	v_add_f32_dpp v17, v17, v17 quad_perm:[1,0,3,2] row_mask:0xf bank_mask:0xf bound_ctrl:1
	s_nop 1
	v_add_f32_dpp v17, v17, v17 quad_perm:[2,3,0,1] row_mask:0xf bank_mask:0xf bound_ctrl:1
	v_sub_f32_e32 v17, v18, v17
	s_and_saveexec_b64 s[0:1], vcc
	v_mul_f32_e32 v18, v0, v17
	v_cvt_pk_bf16_f32 v18, v18, s0
	ds_write_b16 v1, v18 offset:6912
	s_or_b64 exec, exec, s[0:1]
	v_cndmask_b32_e32 v17, 0, v17, vcc
	v_cmp_eq_u32_e64 s[0:1], 49, v2
	s_waitcnt lgkmcnt(4)
	v_fma_f32 v18, v4, v100, 0
	v_fmac_f32_e32 v18, v5, v101
	v_fmac_f32_e32 v18, v6, v102
	v_fmac_f32_e32 v18, v7, v103
	s_waitcnt lgkmcnt(3)
	v_fmac_f32_e32 v18, v8, v104
	v_fmac_f32_e32 v18, v9, v105
	v_fmac_f32_e32 v18, v10, v106
	v_fmac_f32_e32 v18, v11, v107
	s_waitcnt lgkmcnt(2)
	v_fmac_f32_e32 v18, v12, v108
	v_fmac_f32_e32 v18, v13, v109
	v_fmac_f32_e32 v18, v14, v110
	v_fmac_f32_e32 v18, v15, v111
	s_waitcnt lgkmcnt(1)
	v_fmac_f32_e32 v18, v17, v112
	v_fmac_f32_e32 v18, 0, v113
	v_fmac_f32_e32 v18, 0, v114
	v_fmac_f32_e32 v18, 0, v115
	ds_read_b128 v[100:103], v3 offset:12800
	ds_read_b128 v[104:107], v3 offset:12816
	ds_read_b128 v[108:111], v3 offset:12832
	ds_read_b128 v[112:115], v3 offset:12848
	v_cndmask_b32_e64 v19, 0, 1.0, s[0:1]
	s_nop 0
	v_add_f32_dpp v18, v18, v18 quad_perm:[1,0,3,2] row_mask:0xf bank_mask:0xf bound_ctrl:1
	s_nop 1
	v_add_f32_dpp v18, v18, v18 quad_perm:[2,3,0,1] row_mask:0xf bank_mask:0xf bound_ctrl:1
	v_sub_f32_e32 v18, v19, v18
	s_and_saveexec_b64 s[0:1], vcc
	v_mul_f32_e32 v19, v0, v18
	v_cvt_pk_bf16_f32 v19, v19, s0
	ds_write_b16 v1, v19 offset:7056
	s_or_b64 exec, exec, s[0:1]
	v_cndmask_b32_e64 v17, v17, v18, s[4:5]
	v_cmp_eq_u32_e64 s[0:1], 50, v2
	s_waitcnt lgkmcnt(4)
	v_fma_f32 v18, v4, v100, 0
	v_fmac_f32_e32 v18, v5, v101
	v_fmac_f32_e32 v18, v6, v102
	v_fmac_f32_e32 v18, v7, v103
	s_waitcnt lgkmcnt(3)
	v_fmac_f32_e32 v18, v8, v104
	v_fmac_f32_e32 v18, v9, v105
	v_fmac_f32_e32 v18, v10, v106
	v_fmac_f32_e32 v18, v11, v107
	s_waitcnt lgkmcnt(2)
	v_fmac_f32_e32 v18, v12, v108
	v_fmac_f32_e32 v18, v13, v109
	v_fmac_f32_e32 v18, v14, v110
	v_fmac_f32_e32 v18, v15, v111
	s_waitcnt lgkmcnt(1)
	v_fmac_f32_e32 v18, v17, v112
	v_fmac_f32_e32 v18, 0, v113
	v_fmac_f32_e32 v18, 0, v114
	v_fmac_f32_e32 v18, 0, v115
	ds_read_b128 v[100:103], v3 offset:13056
	ds_read_b128 v[104:107], v3 offset:13072
	ds_read_b128 v[108:111], v3 offset:13088
	ds_read_b128 v[112:115], v3 offset:13104
	v_cndmask_b32_e64 v19, 0, 1.0, s[0:1]
	s_nop 0
	v_add_f32_dpp v18, v18, v18 quad_perm:[1,0,3,2] row_mask:0xf bank_mask:0xf bound_ctrl:1
	s_nop 1
	v_add_f32_dpp v18, v18, v18 quad_perm:[2,3,0,1] row_mask:0xf bank_mask:0xf bound_ctrl:1
	v_sub_f32_e32 v18, v19, v18
	s_and_saveexec_b64 s[0:1], vcc
	v_mul_f32_e32 v19, v0, v18
	v_cvt_pk_bf16_f32 v19, v19, s0
	ds_write_b16 v1, v19 offset:7200
	s_or_b64 exec, exec, s[0:1]
	v_cndmask_b32_e64 v17, v17, v18, s[6:7]
	v_cmp_eq_u32_e64 s[0:1], 51, v2
	s_waitcnt lgkmcnt(4)
	v_fma_f32 v18, v4, v100, 0
	v_fmac_f32_e32 v18, v5, v101
	v_fmac_f32_e32 v18, v6, v102
	v_fmac_f32_e32 v18, v7, v103
	s_waitcnt lgkmcnt(3)
	v_fmac_f32_e32 v18, v8, v104
	v_fmac_f32_e32 v18, v9, v105
	v_fmac_f32_e32 v18, v10, v106
	v_fmac_f32_e32 v18, v11, v107
	s_waitcnt lgkmcnt(2)
	v_fmac_f32_e32 v18, v12, v108
	v_fmac_f32_e32 v18, v13, v109
	v_fmac_f32_e32 v18, v14, v110
	v_fmac_f32_e32 v18, v15, v111
	s_waitcnt lgkmcnt(1)
	v_fmac_f32_e32 v18, v17, v112
	v_fmac_f32_e32 v18, 0, v113
	v_fmac_f32_e32 v18, 0, v114
	v_fmac_f32_e32 v18, 0, v115
	ds_read_b128 v[100:103], v3 offset:13312
	ds_read_b128 v[104:107], v3 offset:13328
	ds_read_b128 v[108:111], v3 offset:13344
	ds_read_b128 v[112:115], v3 offset:13360
	v_cndmask_b32_e64 v19, 0, 1.0, s[0:1]
	s_nop 0
	v_add_f32_dpp v18, v18, v18 quad_perm:[1,0,3,2] row_mask:0xf bank_mask:0xf bound_ctrl:1
	s_nop 1
	v_add_f32_dpp v18, v18, v18 quad_perm:[2,3,0,1] row_mask:0xf bank_mask:0xf bound_ctrl:1
	v_sub_f32_e32 v18, v19, v18
	s_and_saveexec_b64 s[0:1], vcc
	v_mul_f32_e32 v19, v0, v18
	v_cvt_pk_bf16_f32 v19, v19, s0
	ds_write_b16 v1, v19 offset:7344
	s_or_b64 exec, exec, s[0:1]
	v_cndmask_b32_e64 v17, v17, v18, s[8:9]
	v_cmp_eq_u32_e64 s[0:1], 52, v2
	s_waitcnt lgkmcnt(4)
	v_fma_f32 v18, v4, v100, 0
	v_fmac_f32_e32 v18, v5, v101
	v_fmac_f32_e32 v18, v6, v102
	v_fmac_f32_e32 v18, v7, v103
	s_waitcnt lgkmcnt(3)
	v_fmac_f32_e32 v18, v8, v104
	v_fmac_f32_e32 v18, v9, v105
	v_fmac_f32_e32 v18, v10, v106
	v_fmac_f32_e32 v18, v11, v107
	s_waitcnt lgkmcnt(2)
	v_fmac_f32_e32 v18, v12, v108
	v_fmac_f32_e32 v18, v13, v109
	v_fmac_f32_e32 v18, v14, v110
	v_fmac_f32_e32 v18, v15, v111
	s_waitcnt lgkmcnt(1)
	v_fmac_f32_e32 v18, v17, v112
	v_fmac_f32_e32 v18, 0, v113
	v_fmac_f32_e32 v18, 0, v114
	v_fmac_f32_e32 v18, 0, v115
	ds_read_b128 v[100:103], v3 offset:13568
	ds_read_b128 v[104:107], v3 offset:13584
	ds_read_b128 v[108:111], v3 offset:13600
	ds_read_b128 v[112:115], v3 offset:13616
	v_cndmask_b32_e64 v19, 0, 1.0, s[0:1]
	s_nop 0
	v_add_f32_dpp v18, v18, v18 quad_perm:[1,0,3,2] row_mask:0xf bank_mask:0xf bound_ctrl:1
	s_nop 1
	v_add_f32_dpp v18, v18, v18 quad_perm:[2,3,0,1] row_mask:0xf bank_mask:0xf bound_ctrl:1
	v_sub_f32_e32 v18, v19, v18
	s_and_saveexec_b64 s[0:1], vcc
	v_mul_f32_e32 v19, v0, v18
	v_cvt_pk_bf16_f32 v19, v19, s0
	ds_write_b16 v1, v19 offset:7488
	s_or_b64 exec, exec, s[0:1]
	v_cndmask_b32_e32 v18, 0, v18, vcc
	v_cmp_eq_u32_e64 s[0:1], 53, v2
	s_waitcnt lgkmcnt(4)
; DI bf16_t f2bf(float f) { return (bf16_t)(pk2(f, 0.f) & 0xffffu); }
; DI void gdn_pre_unit(const Prm& p, unsigned char* lds0, int u, int tid, int wid, int lane) {
;     ...
;     if (wid < 4) {
;         const int c = 16 * wid + (lane >> 2), pp = lane & 3; const float beta = gL[64 + c];
;         float Tp[16];
; #pragma unroll
;         for (int j = 0; j < 16; ++j) Tp[j] = 0.f;
; #pragma unroll
;         for (int t = 0; t < 64; ++t) { float a = 0.f;
; #pragma unroll
;             for (int j4 = 0; j4 < (t + 15) / 16; ++j4) { const f32x4 av = *(const f32x4*)(AL + t * 64 + pp * 16 + 4 * j4);
;                 a += av.x * Tp[4 * j4]; a += av.y * Tp[4 * j4 + 1]; a += av.z * Tp[4 * j4 + 2]; a += av.w * Tp[4 * j4 + 3]; }
;             a += __int_as_float(__builtin_amdgcn_update_dpp(0, __float_as_int(a), 0xB1, 0xF, 0xF, true));
;             a += __int_as_float(__builtin_amdgcn_update_dpp(0, __float_as_int(a), 0x4E, 0xF, 0xF, true));
;             const float Tt = (t == c ? 1.f : 0.f) - a;
;             if (pp == (t & 3)) Tp[t >> 2] = Tt;
;             if (pp == 0) tbL[t * GT_STR + c] = f2bf(Tt * beta);
;         }
;     }
	v_fma_f32 v19, v4, v100, 0
	v_fmac_f32_e32 v19, v5, v101
	v_fmac_f32_e32 v19, v6, v102
	v_fmac_f32_e32 v19, v7, v103
	s_waitcnt lgkmcnt(3)
	v_fmac_f32_e32 v19, v8, v104
	v_fmac_f32_e32 v19, v9, v105
	v_fmac_f32_e32 v19, v10, v106
	v_fmac_f32_e32 v19, v11, v107
	s_waitcnt lgkmcnt(2)
	v_fmac_f32_e32 v19, v12, v108
	v_fmac_f32_e32 v19, v13, v109
	v_fmac_f32_e32 v19, v14, v110
	v_fmac_f32_e32 v19, v15, v111
	s_waitcnt lgkmcnt(1)
	v_fmac_f32_e32 v19, v17, v112
	v_fmac_f32_e32 v19, v18, v113
	v_fmac_f32_e32 v19, 0, v114
	v_fmac_f32_e32 v19, 0, v115
	ds_read_b128 v[100:103], v3 offset:13824
	ds_read_b128 v[104:107], v3 offset:13840
	ds_read_b128 v[108:111], v3 offset:13856
	ds_read_b128 v[112:115], v3 offset:13872
	v_cndmask_b32_e64 v20, 0, 1.0, s[0:1]
	s_nop 0
	v_add_f32_dpp v19, v19, v19 quad_perm:[1,0,3,2] row_mask:0xf bank_mask:0xf bound_ctrl:1
	s_nop 1
	v_add_f32_dpp v19, v19, v19 quad_perm:[2,3,0,1] row_mask:0xf bank_mask:0xf bound_ctrl:1
	v_sub_f32_e32 v19, v20, v19
	s_and_saveexec_b64 s[0:1], vcc
	v_mul_f32_e32 v20, v0, v19
	v_cvt_pk_bf16_f32 v20, v20, s0
	ds_write_b16 v1, v20 offset:7632
	s_or_b64 exec, exec, s[0:1]
	v_cndmask_b32_e64 v18, v18, v19, s[4:5]
	v_cmp_eq_u32_e64 s[0:1], 54, v2
	s_waitcnt lgkmcnt(4)
	v_fma_f32 v19, v4, v100, 0
	v_fmac_f32_e32 v19, v5, v101
	v_fmac_f32_e32 v19, v6, v102
	v_fmac_f32_e32 v19, v7, v103
	s_waitcnt lgkmcnt(3)
	v_fmac_f32_e32 v19, v8, v104
	v_fmac_f32_e32 v19, v9, v105
	v_fmac_f32_e32 v19, v10, v106
	v_fmac_f32_e32 v19, v11, v107
	s_waitcnt lgkmcnt(2)
	v_fmac_f32_e32 v19, v12, v108
	v_fmac_f32_e32 v19, v13, v109
	v_fmac_f32_e32 v19, v14, v110
	v_fmac_f32_e32 v19, v15, v111
	s_waitcnt lgkmcnt(1)
	v_fmac_f32_e32 v19, v17, v112
	v_fmac_f32_e32 v19, v18, v113
	v_fmac_f32_e32 v19, 0, v114
	v_fmac_f32_e32 v19, 0, v115
	ds_read_b128 v[100:103], v3 offset:14080
	ds_read_b128 v[104:107], v3 offset:14096
	ds_read_b128 v[108:111], v3 offset:14112
	ds_read_b128 v[112:115], v3 offset:14128
	v_cndmask_b32_e64 v20, 0, 1.0, s[0:1]
	s_nop 0
	v_add_f32_dpp v19, v19, v19 quad_perm:[1,0,3,2] row_mask:0xf bank_mask:0xf bound_ctrl:1
	s_nop 1
	v_add_f32_dpp v19, v19, v19 quad_perm:[2,3,0,1] row_mask:0xf bank_mask:0xf bound_ctrl:1
	v_sub_f32_e32 v19, v20, v19
	s_and_saveexec_b64 s[0:1], vcc
	v_mul_f32_e32 v20, v0, v19
	v_cvt_pk_bf16_f32 v20, v20, s0
	ds_write_b16 v1, v20 offset:7776
	s_or_b64 exec, exec, s[0:1]
	v_cndmask_b32_e64 v18, v18, v19, s[6:7]
	v_cmp_eq_u32_e64 s[0:1], 55, v2
	s_waitcnt lgkmcnt(4)
	v_fma_f32 v19, v4, v100, 0
	v_fmac_f32_e32 v19, v5, v101
	v_fmac_f32_e32 v19, v6, v102
	v_fmac_f32_e32 v19, v7, v103
	s_waitcnt lgkmcnt(3)
	v_fmac_f32_e32 v19, v8, v104
	v_fmac_f32_e32 v19, v9, v105
	v_fmac_f32_e32 v19, v10, v106
	v_fmac_f32_e32 v19, v11, v107
	s_waitcnt lgkmcnt(2)
	v_fmac_f32_e32 v19, v12, v108
	v_fmac_f32_e32 v19, v13, v109
	v_fmac_f32_e32 v19, v14, v110
	v_fmac_f32_e32 v19, v15, v111
	s_waitcnt lgkmcnt(1)
	v_fmac_f32_e32 v19, v17, v112
	v_fmac_f32_e32 v19, v18, v113
	v_fmac_f32_e32 v19, 0, v114
	v_fmac_f32_e32 v19, 0, v115
	ds_read_b128 v[100:103], v3 offset:14336
	ds_read_b128 v[104:107], v3 offset:14352
	ds_read_b128 v[108:111], v3 offset:14368
	ds_read_b128 v[112:115], v3 offset:14384
	v_cndmask_b32_e64 v20, 0, 1.0, s[0:1]
	s_nop 0
	v_add_f32_dpp v19, v19, v19 quad_perm:[1,0,3,2] row_mask:0xf bank_mask:0xf bound_ctrl:1
	s_nop 1
	v_add_f32_dpp v19, v19, v19 quad_perm:[2,3,0,1] row_mask:0xf bank_mask:0xf bound_ctrl:1
	v_sub_f32_e32 v19, v20, v19
	s_and_saveexec_b64 s[0:1], vcc
	v_mul_f32_e32 v20, v0, v19
	v_cvt_pk_bf16_f32 v20, v20, s0
	ds_write_b16 v1, v20 offset:7920
	s_or_b64 exec, exec, s[0:1]
	v_cndmask_b32_e64 v18, v18, v19, s[8:9]
	v_cmp_eq_u32_e64 s[0:1], 56, v2
	s_waitcnt lgkmcnt(4)
	v_fma_f32 v19, v4, v100, 0
	v_fmac_f32_e32 v19, v5, v101
	v_fmac_f32_e32 v19, v6, v102
	v_fmac_f32_e32 v19, v7, v103
	s_waitcnt lgkmcnt(3)
	v_fmac_f32_e32 v19, v8, v104
	v_fmac_f32_e32 v19, v9, v105
	v_fmac_f32_e32 v19, v10, v106
	v_fmac_f32_e32 v19, v11, v107
	s_waitcnt lgkmcnt(2)
	v_fmac_f32_e32 v19, v12, v108
	v_fmac_f32_e32 v19, v13, v109
	v_fmac_f32_e32 v19, v14, v110
	v_fmac_f32_e32 v19, v15, v111
	s_waitcnt lgkmcnt(1)
	v_fmac_f32_e32 v19, v17, v112
	v_fmac_f32_e32 v19, v18, v113
	v_fmac_f32_e32 v19, 0, v114
	v_fmac_f32_e32 v19, 0, v115
	ds_read_b128 v[100:103], v3 offset:14592
	ds_read_b128 v[104:107], v3 offset:14608
	ds_read_b128 v[108:111], v3 offset:14624
	ds_read_b128 v[112:115], v3 offset:14640
	v_cndmask_b32_e64 v20, 0, 1.0, s[0:1]
	s_nop 0
	v_add_f32_dpp v19, v19, v19 quad_perm:[1,0,3,2] row_mask:0xf bank_mask:0xf bound_ctrl:1
	s_nop 1
	v_add_f32_dpp v19, v19, v19 quad_perm:[2,3,0,1] row_mask:0xf bank_mask:0xf bound_ctrl:1
	v_sub_f32_e32 v19, v20, v19
	s_and_saveexec_b64 s[0:1], vcc
	v_mul_f32_e32 v20, v0, v19
	v_cvt_pk_bf16_f32 v20, v20, s0
	ds_write_b16 v1, v20 offset:8064
	s_or_b64 exec, exec, s[0:1]
	v_cndmask_b32_e32 v19, 0, v19, vcc
	v_cmp_eq_u32_e64 s[0:1], 57, v2
	s_waitcnt lgkmcnt(4)
	v_fma_f32 v20, v4, v100, 0
	v_fmac_f32_e32 v20, v5, v101
	v_fmac_f32_e32 v20, v6, v102
	v_fmac_f32_e32 v20, v7, v103
	s_waitcnt lgkmcnt(3)
	v_fmac_f32_e32 v20, v8, v104
	v_fmac_f32_e32 v20, v9, v105
	v_fmac_f32_e32 v20, v10, v106
	v_fmac_f32_e32 v20, v11, v107
	s_waitcnt lgkmcnt(2)
	v_fmac_f32_e32 v20, v12, v108
	v_fmac_f32_e32 v20, v13, v109
	v_fmac_f32_e32 v20, v14, v110
	v_fmac_f32_e32 v20, v15, v111
	s_waitcnt lgkmcnt(1)
; DI bf16_t f2bf(float f) { return (bf16_t)(pk2(f, 0.f) & 0xffffu); }
; DI void gdn_pre_unit(const Prm& p, unsigned char* lds0, int u, int tid, int wid, int lane) {
;     ...
;     if (wid < 4) {
;         const int c = 16 * wid + (lane >> 2), pp = lane & 3; const float beta = gL[64 + c];
;         float Tp[16];
; #pragma unroll
;         for (int j = 0; j < 16; ++j) Tp[j] = 0.f;
; #pragma unroll
;         for (int t = 0; t < 64; ++t) { float a = 0.f;
; #pragma unroll
;             for (int j4 = 0; j4 < (t + 15) / 16; ++j4) { const f32x4 av = *(const f32x4*)(AL + t * 64 + pp * 16 + 4 * j4);
;                 a += av.x * Tp[4 * j4]; a += av.y * Tp[4 * j4 + 1]; a += av.z * Tp[4 * j4 + 2]; a += av.w * Tp[4 * j4 + 3]; }
;             a += __int_as_float(__builtin_amdgcn_update_dpp(0, __float_as_int(a), 0xB1, 0xF, 0xF, true));
;             a += __int_as_float(__builtin_amdgcn_update_dpp(0, __float_as_int(a), 0x4E, 0xF, 0xF, true));
;             const float Tt = (t == c ? 1.f : 0.f) - a;
;             if (pp == (t & 3)) Tp[t >> 2] = Tt;
;             if (pp == 0) tbL[t * GT_STR + c] = f2bf(Tt * beta);
;         }
;     }
	v_fmac_f32_e32 v20, v17, v112
	v_fmac_f32_e32 v20, v18, v113
	v_fmac_f32_e32 v20, v19, v114
	v_fmac_f32_e32 v20, 0, v115
	ds_read_b128 v[100:103], v3 offset:14848
	ds_read_b128 v[104:107], v3 offset:14864
	ds_read_b128 v[108:111], v3 offset:14880
	ds_read_b128 v[112:115], v3 offset:14896
	v_cndmask_b32_e64 v21, 0, 1.0, s[0:1]
	s_nop 0
	v_add_f32_dpp v20, v20, v20 quad_perm:[1,0,3,2] row_mask:0xf bank_mask:0xf bound_ctrl:1
	s_nop 1
	v_add_f32_dpp v20, v20, v20 quad_perm:[2,3,0,1] row_mask:0xf bank_mask:0xf bound_ctrl:1
	v_sub_f32_e32 v20, v21, v20
	s_and_saveexec_b64 s[0:1], vcc
	v_mul_f32_e32 v21, v0, v20
	v_cvt_pk_bf16_f32 v21, v21, s0
	ds_write_b16 v1, v21 offset:8208
	s_or_b64 exec, exec, s[0:1]
	v_cndmask_b32_e64 v19, v19, v20, s[4:5]
	v_cmp_eq_u32_e64 s[0:1], 58, v2
	s_waitcnt lgkmcnt(4)
	v_fma_f32 v20, v4, v100, 0
	v_fmac_f32_e32 v20, v5, v101
	v_fmac_f32_e32 v20, v6, v102
	v_fmac_f32_e32 v20, v7, v103
	s_waitcnt lgkmcnt(3)
	v_fmac_f32_e32 v20, v8, v104
	v_fmac_f32_e32 v20, v9, v105
	v_fmac_f32_e32 v20, v10, v106
	v_fmac_f32_e32 v20, v11, v107
	s_waitcnt lgkmcnt(2)
	v_fmac_f32_e32 v20, v12, v108
	v_fmac_f32_e32 v20, v13, v109
	v_fmac_f32_e32 v20, v14, v110
	v_fmac_f32_e32 v20, v15, v111
	s_waitcnt lgkmcnt(1)
	v_fmac_f32_e32 v20, v17, v112
	v_fmac_f32_e32 v20, v18, v113
	v_fmac_f32_e32 v20, v19, v114
	v_fmac_f32_e32 v20, 0, v115
	ds_read_b128 v[100:103], v3 offset:15104
	ds_read_b128 v[104:107], v3 offset:15120
	ds_read_b128 v[108:111], v3 offset:15136
	ds_read_b128 v[112:115], v3 offset:15152
	v_cndmask_b32_e64 v21, 0, 1.0, s[0:1]
	s_nop 0
	v_add_f32_dpp v20, v20, v20 quad_perm:[1,0,3,2] row_mask:0xf bank_mask:0xf bound_ctrl:1
	s_nop 1
	v_add_f32_dpp v20, v20, v20 quad_perm:[2,3,0,1] row_mask:0xf bank_mask:0xf bound_ctrl:1
	v_sub_f32_e32 v20, v21, v20
	s_and_saveexec_b64 s[0:1], vcc
	v_mul_f32_e32 v21, v0, v20
	v_cvt_pk_bf16_f32 v21, v21, s0
	ds_write_b16 v1, v21 offset:8352
	s_or_b64 exec, exec, s[0:1]
	v_cndmask_b32_e64 v19, v19, v20, s[6:7]
	v_cmp_eq_u32_e64 s[0:1], 59, v2
	s_waitcnt lgkmcnt(4)
	v_fma_f32 v20, v4, v100, 0
	v_fmac_f32_e32 v20, v5, v101
	v_fmac_f32_e32 v20, v6, v102
	v_fmac_f32_e32 v20, v7, v103
	s_waitcnt lgkmcnt(3)
	v_fmac_f32_e32 v20, v8, v104
	v_fmac_f32_e32 v20, v9, v105
	v_fmac_f32_e32 v20, v10, v106
	v_fmac_f32_e32 v20, v11, v107
	s_waitcnt lgkmcnt(2)
	v_fmac_f32_e32 v20, v12, v108
	v_fmac_f32_e32 v20, v13, v109
	v_fmac_f32_e32 v20, v14, v110
	v_fmac_f32_e32 v20, v15, v111
	s_waitcnt lgkmcnt(1)
	v_fmac_f32_e32 v20, v17, v112
	v_fmac_f32_e32 v20, v18, v113
	v_fmac_f32_e32 v20, v19, v114
	v_fmac_f32_e32 v20, 0, v115
	ds_read_b128 v[100:103], v3 offset:15360
	ds_read_b128 v[104:107], v3 offset:15376
	ds_read_b128 v[108:111], v3 offset:15392
	ds_read_b128 v[112:115], v3 offset:15408
	v_cndmask_b32_e64 v21, 0, 1.0, s[0:1]
	s_nop 0
	v_add_f32_dpp v20, v20, v20 quad_perm:[1,0,3,2] row_mask:0xf bank_mask:0xf bound_ctrl:1
	s_nop 1
	v_add_f32_dpp v20, v20, v20 quad_perm:[2,3,0,1] row_mask:0xf bank_mask:0xf bound_ctrl:1
	v_sub_f32_e32 v20, v21, v20
	s_and_saveexec_b64 s[0:1], vcc
	v_mul_f32_e32 v21, v0, v20
	v_cvt_pk_bf16_f32 v21, v21, s0
	ds_write_b16 v1, v21 offset:8496
	s_or_b64 exec, exec, s[0:1]
	v_cndmask_b32_e64 v19, v19, v20, s[8:9]
	v_cmp_eq_u32_e64 s[0:1], 60, v2
	s_waitcnt lgkmcnt(4)
	v_fma_f32 v20, v4, v100, 0
	v_fmac_f32_e32 v20, v5, v101
	v_fmac_f32_e32 v20, v6, v102
	v_fmac_f32_e32 v20, v7, v103
	s_waitcnt lgkmcnt(3)
	v_fmac_f32_e32 v20, v8, v104
	v_fmac_f32_e32 v20, v9, v105
	v_fmac_f32_e32 v20, v10, v106
	v_fmac_f32_e32 v20, v11, v107
	s_waitcnt lgkmcnt(2)
	v_fmac_f32_e32 v20, v12, v108
	v_fmac_f32_e32 v20, v13, v109
	v_fmac_f32_e32 v20, v14, v110
	v_fmac_f32_e32 v20, v15, v111
	s_waitcnt lgkmcnt(1)
; DI bf16_t f2bf(float f) { return (bf16_t)(pk2(f, 0.f) & 0xffffu); }
; DI void gdn_pre_unit(const Prm& p, unsigned char* lds0, int u, int tid, int wid, int lane) {
;     ...
;     if (wid < 4) {
;         const int c = 16 * wid + (lane >> 2), pp = lane & 3; const float beta = gL[64 + c];
;         float Tp[16];
; #pragma unroll
;         for (int j = 0; j < 16; ++j) Tp[j] = 0.f;
; #pragma unroll
;         for (int t = 0; t < 64; ++t) { float a = 0.f;
; #pragma unroll
;             for (int j4 = 0; j4 < (t + 15) / 16; ++j4) { const f32x4 av = *(const f32x4*)(AL + t * 64 + pp * 16 + 4 * j4);
;                 a += av.x * Tp[4 * j4]; a += av.y * Tp[4 * j4 + 1]; a += av.z * Tp[4 * j4 + 2]; a += av.w * Tp[4 * j4 + 3]; }
;             a += __int_as_float(__builtin_amdgcn_update_dpp(0, __float_as_int(a), 0xB1, 0xF, 0xF, true));
;             a += __int_as_float(__builtin_amdgcn_update_dpp(0, __float_as_int(a), 0x4E, 0xF, 0xF, true));
;             const float Tt = (t == c ? 1.f : 0.f) - a;
;             if (pp == (t & 3)) Tp[t >> 2] = Tt;
;             if (pp == 0) tbL[t * GT_STR + c] = f2bf(Tt * beta);
;         }
;     }
	v_fmac_f32_e32 v20, v17, v112
	v_fmac_f32_e32 v20, v18, v113
	v_fmac_f32_e32 v20, v19, v114
	v_fmac_f32_e32 v20, 0, v115
	ds_read_b128 v[100:103], v3 offset:15616
	ds_read_b128 v[104:107], v3 offset:15632
	ds_read_b128 v[108:111], v3 offset:15648
	ds_read_b128 v[112:115], v3 offset:15664
	v_cndmask_b32_e64 v21, 0, 1.0, s[0:1]
	s_nop 0
	v_add_f32_dpp v20, v20, v20 quad_perm:[1,0,3,2] row_mask:0xf bank_mask:0xf bound_ctrl:1
	s_nop 1
	v_add_f32_dpp v20, v20, v20 quad_perm:[2,3,0,1] row_mask:0xf bank_mask:0xf bound_ctrl:1
	v_sub_f32_e32 v20, v21, v20
	s_and_saveexec_b64 s[0:1], vcc
	v_mul_f32_e32 v21, v0, v20
	v_cvt_pk_bf16_f32 v21, v21, s0
	ds_write_b16 v1, v21 offset:8640
	s_or_b64 exec, exec, s[0:1]
	v_cndmask_b32_e32 v20, 0, v20, vcc
	v_cmp_eq_u32_e64 s[0:1], 61, v2
	s_waitcnt lgkmcnt(4)
	v_fma_f32 v21, v4, v100, 0
	v_fmac_f32_e32 v21, v5, v101
	v_fmac_f32_e32 v21, v6, v102
	v_fmac_f32_e32 v21, v7, v103
	s_waitcnt lgkmcnt(3)
	v_fmac_f32_e32 v21, v8, v104
	v_fmac_f32_e32 v21, v9, v105
	v_fmac_f32_e32 v21, v10, v106
	v_fmac_f32_e32 v21, v11, v107
	s_waitcnt lgkmcnt(2)
	v_fmac_f32_e32 v21, v12, v108
	v_fmac_f32_e32 v21, v13, v109
	v_fmac_f32_e32 v21, v14, v110
	v_fmac_f32_e32 v21, v15, v111
	s_waitcnt lgkmcnt(1)
	v_fmac_f32_e32 v21, v17, v112
	v_fmac_f32_e32 v21, v18, v113
	v_fmac_f32_e32 v21, v19, v114
	v_fmac_f32_e32 v21, v20, v115
	ds_read_b128 v[100:103], v3 offset:15872
	ds_read_b128 v[104:107], v3 offset:15888
	ds_read_b128 v[108:111], v3 offset:15904
	ds_read_b128 v[112:115], v3 offset:15920
	v_cndmask_b32_e64 v22, 0, 1.0, s[0:1]
	s_nop 0
	v_add_f32_dpp v21, v21, v21 quad_perm:[1,0,3,2] row_mask:0xf bank_mask:0xf bound_ctrl:1
	s_nop 1
	v_add_f32_dpp v21, v21, v21 quad_perm:[2,3,0,1] row_mask:0xf bank_mask:0xf bound_ctrl:1
	v_sub_f32_e32 v21, v22, v21
	s_and_saveexec_b64 s[0:1], vcc
	v_mul_f32_e32 v22, v0, v21
	v_cvt_pk_bf16_f32 v22, v22, s0
	ds_write_b16 v1, v22 offset:8784
	s_or_b64 exec, exec, s[0:1]
	v_cndmask_b32_e64 v20, v20, v21, s[4:5]
	v_cmp_eq_u32_e64 s[0:1], 62, v2
	s_waitcnt lgkmcnt(4)
	v_fma_f32 v21, v4, v100, 0
	v_fmac_f32_e32 v21, v5, v101
	v_fmac_f32_e32 v21, v6, v102
	v_fmac_f32_e32 v21, v7, v103
	s_waitcnt lgkmcnt(3)
	v_fmac_f32_e32 v21, v8, v104
	v_fmac_f32_e32 v21, v9, v105
	v_fmac_f32_e32 v21, v10, v106
	v_fmac_f32_e32 v21, v11, v107
	s_waitcnt lgkmcnt(2)
	v_fmac_f32_e32 v21, v12, v108
	v_fmac_f32_e32 v21, v13, v109
	v_fmac_f32_e32 v21, v14, v110
	v_fmac_f32_e32 v21, v15, v111
	s_waitcnt lgkmcnt(1)
	v_fmac_f32_e32 v21, v17, v112
	v_fmac_f32_e32 v21, v18, v113
	v_fmac_f32_e32 v21, v19, v114
	v_fmac_f32_e32 v21, v20, v115
	ds_read_b128 v[100:103], v3 offset:16128
	ds_read_b128 v[104:107], v3 offset:16144
	ds_read_b128 v[108:111], v3 offset:16160
	ds_read_b128 v[112:115], v3 offset:16176
	v_cndmask_b32_e64 v22, 0, 1.0, s[0:1]
	s_nop 0
	v_add_f32_dpp v21, v21, v21 quad_perm:[1,0,3,2] row_mask:0xf bank_mask:0xf bound_ctrl:1
	s_nop 1
	v_add_f32_dpp v21, v21, v21 quad_perm:[2,3,0,1] row_mask:0xf bank_mask:0xf bound_ctrl:1
	v_sub_f32_e32 v21, v22, v21
	s_and_saveexec_b64 s[0:1], vcc
	v_mul_f32_e32 v22, v0, v21
	v_cvt_pk_bf16_f32 v22, v22, s0
	ds_write_b16 v1, v22 offset:8928
	s_or_b64 exec, exec, s[0:1]
	v_cndmask_b32_e64 v20, v20, v21, s[6:7]
	s_waitcnt lgkmcnt(4)
	v_fma_f32 v3, v4, v100, 0
	v_fmac_f32_e32 v3, v5, v101
	v_fmac_f32_e32 v3, v6, v102
	v_fmac_f32_e32 v3, v7, v103
	s_waitcnt lgkmcnt(3)
	v_fmac_f32_e32 v3, v8, v104
	v_fmac_f32_e32 v3, v9, v105
	v_fmac_f32_e32 v3, v10, v106
	v_fmac_f32_e32 v3, v11, v107
	s_waitcnt lgkmcnt(2)
	v_fmac_f32_e32 v3, v12, v108
	v_fmac_f32_e32 v3, v13, v109
	v_fmac_f32_e32 v3, v14, v110
	v_fmac_f32_e32 v3, v15, v111
	s_waitcnt lgkmcnt(1)
	v_fmac_f32_e32 v3, v17, v112
	v_fmac_f32_e32 v3, v18, v113
	v_fmac_f32_e32 v3, v19, v114
	v_fmac_f32_e32 v3, v20, v115
	s_nop 1
	v_add_f32_dpp v3, v3, v3 quad_perm:[1,0,3,2] row_mask:0xf bank_mask:0xf bound_ctrl:1
	s_nop 1
	v_mov_b32_dpp v4, v3 quad_perm:[2,3,0,1] row_mask:0xf bank_mask:0xf bound_ctrl:1
	s_and_saveexec_b64 s[0:1], vcc
	s_cbranch_execz .LBB0_1626
	v_cmp_eq_u32_e32 vcc, 63, v2
	v_add_f32_e32 v3, v3, v4
	s_nop 0
	v_cndmask_b32_e64 v2, 0, 1.0, vcc
	v_sub_f32_e32 v2, v2, v3
	v_mul_f32_e32 v0, v0, v2
	v_cvt_pk_bf16_f32 v0, v0, s0
	ds_write_b16 v1, v0 offset:9072

; __device__ __forceinline__ unsigned xb_add(unsigned* p, unsigned v) { return __hip_atomic_fetch_add(p, v, __ATOMIC_RELAXED, __HIP_MEMORY_SCOPE_AGENT); }
; __device__ __forceinline__ void xcd_barrier(const XcdBarrier& b) {
;     asm volatile("s_waitcnt vmcnt(0)" ::: "memory");
;     __syncthreads();
;     if (threadIdx.x == 0) {
;         unsigned* bar = b.bar;
;         __builtin_amdgcn_s_waitcnt(0);
;         unsigned nloc = b.st[0], nx = b.st[1];
;         if (nloc == 0u) { xcd_barrier_complete(bar, b.x, nloc, nx); b.st[0] = nloc; b.st[1] = nx; }
;         const unsigned old = xb_add(&bar[XB_XSUB(b.x)], 1u);
;         const unsigned gen = old / nloc;
;         if (old + 1u == (gen + 1u) * nloc) {
.LBB0_2432:
	s_waitcnt vmcnt(0)
	s_barrier
	s_waitcnt vmcnt(0)
	s_barrier
	s_mov_b64 s[0:1], exec
	v_readlane_b32 s4, v247, 3
	v_readlane_b32 s5, v247, 4
	s_and_b64 s[4:5], s[0:1], s[4:5]
	s_mov_b64 exec, s[4:5]
	s_branch .LBB0_2484
	s_add_i32 s4, 0, 0x23fe0
	v_mov_b32_e32 v0, s4
	s_waitcnt vmcnt(0) expcnt(0) lgkmcnt(0)
	ds_read_b32 v2, v0
	s_add_i32 s4, 0, 0x23fe4
	v_mov_b32_e32 v0, s4
	ds_read_b32 v0, v0
	s_waitcnt lgkmcnt(1)
	v_cmp_ne_u32_e32 vcc, 0, v2
	s_cbranch_vccnz .LBB0_2448
	v_readlane_b32 s4, v247, 1
	v_readlane_b32 s5, v247, 2
	v_readlane_b32 s6, v247, 0
	s_mul_i32 s38, s5, s6
	s_mul_i32 s38, s38, s4
	s_add_u32 s4, s34, 0x101200
	s_addc_u32 s5, s35, 0
	s_add_u32 s6, s34, 0x101400
	s_addc_u32 s7, s35, 0
	s_add_u32 s8, s34, 0x101500
	s_addc_u32 s9, s35, 0
	s_add_u32 s10, s34, 0x101600
	s_addc_u32 s11, s35, 0
	s_add_u32 s12, s34, 0x101700
	s_addc_u32 s13, s35, 0
	s_add_u32 s14, s34, 0x101800
	s_addc_u32 s15, s35, 0
	s_add_u32 s16, s34, 0x101900
	s_addc_u32 s17, s35, 0
	s_add_u32 s18, s34, 0x101a00
	s_addc_u32 s19, s35, 0
	s_add_u32 s20, s34, 0x101b00
	s_addc_u32 s21, s35, 0
	s_add_u32 s22, s34, 0x101c00
	s_addc_u32 s23, s35, 0
	s_add_u32 s24, s34, 0x101d00
	s_addc_u32 s25, s35, 0
	s_add_u32 s26, s34, 0x101e00
	s_addc_u32 s27, s35, 0
	s_add_u32 s36, s34, 0x101f00
	s_addc_u32 s37, s35, 0
	s_add_u32 s40, s34, 0x102000
	s_addc_u32 s41, s35, 0
	s_add_u32 s42, s34, 0x102100
	s_addc_u32 s43, s35, 0
	s_add_u32 s44, s34, 0x102200
	s_addc_u32 s45, s35, 0
	s_add_u32 s46, s34, 0x102300
	s_addc_u32 s47, s35, 0
	s_mov_b32 s39, 1
	v_mov_b32_e32 v16, 0
	s_branch .LBB0_2436
